# scanner: K/V/D/W/B operands prefetched two steps ahead into three register sets (wait first, then issue), dedicated reduce registers
# speedup vs baseline: 1.0156x; 1.0156x over previous
; template <int CTRL> __device__ __forceinline__ float dppf(float x) { return __builtin_bit_cast(float, __builtin_amdgcn_update_dpp(0, __builtin_bit_cast(int, x), CTRL, 0xF, 0xF, false)); }
; __device__ __forceinline__ void phase_rwkv_scan(const Fr& F, int jr) {
;     ...
;                 for (int pg = 0; pg < 64; pg += 16) {
; #pragma unroll
;                     for (int pi = 0; pi < 16; ++pi) {
;                         const int p = pg + pi, pn = p < 63 ? p + 1 : 63;
;                         const f32x4 w4n = PW[pn * 16], k4n = PW[1024 + pn * 16], b4n = PW[2048 + pn * 16], d4n = PW[3072 + pn * 16], r4n = PR[pn * 16];
;                         const float vvn = PV[pn * 32];
;                         f32x2 t = S01 * k4.xy; t = S23 * k4.zw + t; float sa = t.x + t.y;
;                         sa += dppf<0x128>(sa);
;                         const f32x2 dv01 = d4.xy * vv, dv23 = d4.zw * vv;
;                         sa += dppf<0x124>(sa);
;                         const f32x2 e01 = S01 * w4.xy + dv01;
;                         sa += dppf<0x122>(sa);
;                         const f32x2 e23 = S23 * w4.zw + dv23;
;                         sa += dppf<0x121>(sa);
;                         S01 = e01 - b4.xy * sa; S23 = e23 - b4.zw * sa;
;                         f32x2 u = S01 * r4.xy; u = S23 * r4.zw + u;
;                         PY[pi * 64] = u.x + u.y;
;                         w4 = w4n; k4 = k4n; b4 = b4n; d4 = d4n; r4 = r4n; vv = vvn;
;                     }
.Lrw0_shc:
	v_add_u32_e32 v240, s11, v214
	v_add_u32_e32 v242, s11, v216
	ds_read_b128 v[84:87], v240 offset:8704
	ds_read_b64 v[100:101], v242 offset:43520
	ds_read_b128 v[92:95], v240 offset:26112
	ds_read_b128 v[80:83], v240 offset:0
	ds_read_b128 v[88:91], v240 offset:17408
	ds_read_b128 v[96:99], v240 offset:34816
	ds_read_b128 v[106:109], v240 offset:8976
	ds_read_b64 v[118:119], v242 offset:43792
	ds_read_b128 v[114:117], v240 offset:26384
	ds_read_b128 v[102:105], v240 offset:272
	ds_read_b128 v[110:113], v240 offset:17680
	s_lshl_b32 s17, s10, 5
	s_cmp_lt_u32 s10, 8
	s_movk_i32 s18, 0x11ff
	s_cselect_b32 s18, 0xff, s18
	s_sub_i32 s18, s18, s17
	s_cmp_eq_u32 s6, 0
	s_cselect_b32 s15, s17, s18
	s_cselect_b32 s19, 16, -16
	s_waitcnt lgkmcnt(6)
	ds_read_b128 v[4:7], v240 offset:9248
	ds_read_b64 v[16:17], v242 offset:44064
	ds_read_b128 v[12:15], v240 offset:26656
	ds_read_b128 v[0:3], v240 offset:544
	ds_read_b128 v[8:11], v240 offset:17952
	v_pk_mul_f32 v[226:227], v[206:207], v[84:85] op_sel_hi:[1,0]
	v_pk_mul_f32 v[232:233], v[100:101], v[92:93] op_sel_hi:[1,0]
	v_pk_fma_f32 v[226:227], v[208:209], v[84:85], v[226:227] op_sel:[0,1,0]
	v_pk_mul_f32 v[234:235], v[100:101], v[92:93] op_sel:[0,1]
	v_pk_fma_f32 v[226:227], v[210:211], v[86:87], v[226:227] op_sel_hi:[1,0,1]
	v_pk_mul_f32 v[236:237], v[100:101], v[94:95] op_sel_hi:[1,0]
	v_pk_fma_f32 v[226:227], v[212:213], v[86:87], v[226:227] op_sel:[0,1,0]
	v_pk_mul_f32 v[238:239], v[100:101], v[94:95] op_sel:[0,1]
	s_nop 0
	v_add_f32_dpp v230, v227, v226 row_ror:8 row_mask:0xf bank_mask:0xf
	v_pk_fma_f32 v[232:233], v[206:207], v[80:81], v[232:233] op_sel_hi:[1,0,1]
	v_pk_fma_f32 v[234:235], v[208:209], v[80:81], v[234:235] op_sel:[0,1,0]
	v_add_f32_dpp v230, v230, v230 quad_perm:[1,0,3,2] row_mask:0xf bank_mask:0xf
	v_pk_fma_f32 v[236:237], v[210:211], v[82:83], v[236:237] op_sel_hi:[1,0,1]
	v_pk_fma_f32 v[238:239], v[212:213], v[82:83], v[238:239] op_sel:[0,1,0]
	v_add_f32_dpp v230, v230, v230 quad_perm:[2,3,0,1] row_mask:0xf bank_mask:0xf
	ds_read_b128 v[222:225], v240 offset:35088
	s_nop 0
	v_add_f32_dpp v230, v230, v230 row_half_mirror row_mask:0xf bank_mask:0xf
	s_nop 1
	v_mov_b32_dpp v231, v230 row_ror:8 row_mask:0xf bank_mask:0xf
	s_nop 0
	v_pk_fma_f32 v[206:207], v[88:89], v[230:231], v[232:233] op_sel_hi:[0,1,1] neg_lo:[1,0,0] neg_hi:[1,0,0]
	v_pk_fma_f32 v[208:209], v[88:89], v[230:231], v[234:235] op_sel:[1,0,0] neg_lo:[1,0,0] neg_hi:[1,0,0]
	v_pk_fma_f32 v[210:211], v[90:91], v[230:231], v[236:237] op_sel_hi:[0,1,1] neg_lo:[1,0,0] neg_hi:[1,0,0]
	v_pk_fma_f32 v[212:213], v[90:91], v[230:231], v[238:239] op_sel:[1,0,0] neg_lo:[1,0,0] neg_hi:[1,0,0]
	s_waitcnt lgkmcnt(6)
	ds_read_b128 v[84:87], v240 offset:9520
	ds_read_b64 v[100:101], v242 offset:44336
	ds_read_b128 v[92:95], v240 offset:26928
	ds_read_b128 v[80:83], v240 offset:816
	ds_read_b128 v[88:91], v240 offset:18224
	v_pk_mul_f32 v[226:227], v[206:207], v[106:107] op_sel_hi:[1,0]
	v_pk_mul_f32 v[228:229], v[206:207], v[96:97] op_sel_hi:[1,0]
	v_pk_fma_f32 v[226:227], v[208:209], v[106:107], v[226:227] op_sel:[0,1,0]
	v_pk_fma_f32 v[228:229], v[208:209], v[96:97], v[228:229] op_sel:[0,1,0]
	v_pk_fma_f32 v[226:227], v[210:211], v[108:109], v[226:227] op_sel_hi:[1,0,1]
	v_pk_fma_f32 v[228:229], v[210:211], v[98:99], v[228:229] op_sel_hi:[1,0,1]
	v_pk_fma_f32 v[226:227], v[212:213], v[108:109], v[226:227] op_sel:[0,1,0]
	v_pk_fma_f32 v[228:229], v[212:213], v[98:99], v[228:229] op_sel:[0,1,0]
	v_pk_mul_f32 v[232:233], v[118:119], v[114:115] op_sel_hi:[1,0]
	v_add_f32_dpp v230, v227, v226 row_ror:8 row_mask:0xf bank_mask:0xf
	v_pk_mul_f32 v[234:235], v[118:119], v[114:115] op_sel:[0,1]
	v_pk_mul_f32 v[236:237], v[118:119], v[116:117] op_sel_hi:[1,0]
	v_add_f32_dpp v230, v230, v230 quad_perm:[1,0,3,2] row_mask:0xf bank_mask:0xf
	v_pk_mul_f32 v[238:239], v[118:119], v[116:117] op_sel:[0,1]
	ds_read_b128 v[96:99], v240 offset:35360
	v_add_f32_dpp v230, v230, v230 quad_perm:[2,3,0,1] row_mask:0xf bank_mask:0xf
	v_pk_fma_f32 v[232:233], v[206:207], v[102:103], v[232:233] op_sel_hi:[1,0,1]
	v_pk_fma_f32 v[234:235], v[208:209], v[102:103], v[234:235] op_sel:[0,1,0]
	v_add_f32_dpp v230, v230, v230 row_half_mirror row_mask:0xf bank_mask:0xf
	v_pk_fma_f32 v[236:237], v[210:211], v[104:105], v[236:237] op_sel_hi:[1,0,1]
	v_pk_fma_f32 v[238:239], v[212:213], v[104:105], v[238:239] op_sel:[0,1,0]
	v_mov_b32_dpp v231, v230 row_ror:8 row_mask:0xf bank_mask:0xf
	ds_write_b64 v217, v[228:229] offset:0
	v_pk_fma_f32 v[206:207], v[110:111], v[230:231], v[232:233] op_sel_hi:[0,1,1] neg_lo:[1,0,0] neg_hi:[1,0,0]
	v_pk_fma_f32 v[208:209], v[110:111], v[230:231], v[234:235] op_sel:[1,0,0] neg_lo:[1,0,0] neg_hi:[1,0,0]
	v_pk_fma_f32 v[210:211], v[112:113], v[230:231], v[236:237] op_sel_hi:[0,1,1] neg_lo:[1,0,0] neg_hi:[1,0,0]
	v_pk_fma_f32 v[212:213], v[112:113], v[230:231], v[238:239] op_sel:[1,0,0] neg_lo:[1,0,0] neg_hi:[1,0,0]
	s_waitcnt lgkmcnt(7)
; template <int CTRL> __device__ __forceinline__ float dppf(float x) { return __builtin_bit_cast(float, __builtin_amdgcn_update_dpp(0, __builtin_bit_cast(int, x), CTRL, 0xF, 0xF, false)); }
; __device__ __forceinline__ void phase_rwkv_scan(const Fr& F, int jr) {
;     ...
;                 for (int pg = 0; pg < 64; pg += 16) {
; #pragma unroll
;                     for (int pi = 0; pi < 16; ++pi) {
;                         const int p = pg + pi, pn = p < 63 ? p + 1 : 63;
;                         const f32x4 w4n = PW[pn * 16], k4n = PW[1024 + pn * 16], b4n = PW[2048 + pn * 16], d4n = PW[3072 + pn * 16], r4n = PR[pn * 16];
;                         const float vvn = PV[pn * 32];
;                         f32x2 t = S01 * k4.xy; t = S23 * k4.zw + t; float sa = t.x + t.y;
;                         sa += dppf<0x128>(sa);
;                         const f32x2 dv01 = d4.xy * vv, dv23 = d4.zw * vv;
;                         sa += dppf<0x124>(sa);
;                         const f32x2 e01 = S01 * w4.xy + dv01;
;                         sa += dppf<0x122>(sa);
;                         const f32x2 e23 = S23 * w4.zw + dv23;
;                         sa += dppf<0x121>(sa);
;                         S01 = e01 - b4.xy * sa; S23 = e23 - b4.zw * sa;
;                         f32x2 u = S01 * r4.xy; u = S23 * r4.zw + u;
;                         PY[pi * 64] = u.x + u.y;
;                         w4 = w4n; k4 = k4n; b4 = b4n; d4 = d4n; r4 = r4n; vv = vvn;
;                     }
	ds_read_b128 v[106:109], v240 offset:9792
	ds_read_b64 v[118:119], v242 offset:44608
	ds_read_b128 v[114:117], v240 offset:27200
	ds_read_b128 v[102:105], v240 offset:1088
	ds_read_b128 v[110:113], v240 offset:18496
	v_pk_mul_f32 v[226:227], v[206:207], v[4:5] op_sel_hi:[1,0]
	v_pk_mul_f32 v[228:229], v[206:207], v[222:223] op_sel_hi:[1,0]
	v_pk_fma_f32 v[226:227], v[208:209], v[4:5], v[226:227] op_sel:[0,1,0]
	v_pk_fma_f32 v[228:229], v[208:209], v[222:223], v[228:229] op_sel:[0,1,0]
	v_pk_fma_f32 v[226:227], v[210:211], v[6:7], v[226:227] op_sel_hi:[1,0,1]
	v_pk_fma_f32 v[228:229], v[210:211], v[224:225], v[228:229] op_sel_hi:[1,0,1]
	v_pk_fma_f32 v[226:227], v[212:213], v[6:7], v[226:227] op_sel:[0,1,0]
	v_pk_fma_f32 v[228:229], v[212:213], v[224:225], v[228:229] op_sel:[0,1,0]
	v_pk_mul_f32 v[232:233], v[16:17], v[12:13] op_sel_hi:[1,0]
	v_add_f32_dpp v230, v227, v226 row_ror:8 row_mask:0xf bank_mask:0xf
	v_pk_mul_f32 v[234:235], v[16:17], v[12:13] op_sel:[0,1]
	v_pk_mul_f32 v[236:237], v[16:17], v[14:15] op_sel_hi:[1,0]
	v_add_f32_dpp v230, v230, v230 quad_perm:[1,0,3,2] row_mask:0xf bank_mask:0xf
	v_pk_mul_f32 v[238:239], v[16:17], v[14:15] op_sel:[0,1]
	ds_read_b128 v[222:225], v240 offset:35632
	v_add_f32_dpp v230, v230, v230 quad_perm:[2,3,0,1] row_mask:0xf bank_mask:0xf
	v_pk_fma_f32 v[232:233], v[206:207], v[0:1], v[232:233] op_sel_hi:[1,0,1]
	v_pk_fma_f32 v[234:235], v[208:209], v[0:1], v[234:235] op_sel:[0,1,0]
	v_add_f32_dpp v230, v230, v230 row_half_mirror row_mask:0xf bank_mask:0xf
	v_pk_fma_f32 v[236:237], v[210:211], v[2:3], v[236:237] op_sel_hi:[1,0,1]
	v_pk_fma_f32 v[238:239], v[212:213], v[2:3], v[238:239] op_sel:[0,1,0]
	v_mov_b32_dpp v231, v230 row_ror:8 row_mask:0xf bank_mask:0xf
	ds_write_b64 v217, v[228:229] offset:576
	v_pk_fma_f32 v[206:207], v[8:9], v[230:231], v[232:233] op_sel_hi:[0,1,1] neg_lo:[1,0,0] neg_hi:[1,0,0]
	v_pk_fma_f32 v[208:209], v[8:9], v[230:231], v[234:235] op_sel:[1,0,0] neg_lo:[1,0,0] neg_hi:[1,0,0]
	v_pk_fma_f32 v[210:211], v[10:11], v[230:231], v[236:237] op_sel_hi:[0,1,1] neg_lo:[1,0,0] neg_hi:[1,0,0]
	v_pk_fma_f32 v[212:213], v[10:11], v[230:231], v[238:239] op_sel:[1,0,0] neg_lo:[1,0,0] neg_hi:[1,0,0]
	s_waitcnt lgkmcnt(8)
	ds_read_b128 v[4:7], v240 offset:10064
	ds_read_b64 v[16:17], v242 offset:44880
	ds_read_b128 v[12:15], v240 offset:27472
	ds_read_b128 v[0:3], v240 offset:1360
	ds_read_b128 v[8:11], v240 offset:18768
	v_pk_mul_f32 v[226:227], v[206:207], v[84:85] op_sel_hi:[1,0]
	v_pk_mul_f32 v[228:229], v[206:207], v[96:97] op_sel_hi:[1,0]
	v_pk_fma_f32 v[226:227], v[208:209], v[84:85], v[226:227] op_sel:[0,1,0]
	v_pk_fma_f32 v[228:229], v[208:209], v[96:97], v[228:229] op_sel:[0,1,0]
	v_pk_fma_f32 v[226:227], v[210:211], v[86:87], v[226:227] op_sel_hi:[1,0,1]
	v_pk_fma_f32 v[228:229], v[210:211], v[98:99], v[228:229] op_sel_hi:[1,0,1]
	v_pk_fma_f32 v[226:227], v[212:213], v[86:87], v[226:227] op_sel:[0,1,0]
	v_pk_fma_f32 v[228:229], v[212:213], v[98:99], v[228:229] op_sel:[0,1,0]
	v_pk_mul_f32 v[232:233], v[100:101], v[92:93] op_sel_hi:[1,0]
	v_add_f32_dpp v230, v227, v226 row_ror:8 row_mask:0xf bank_mask:0xf
	v_pk_mul_f32 v[234:235], v[100:101], v[92:93] op_sel:[0,1]
	v_pk_mul_f32 v[236:237], v[100:101], v[94:95] op_sel_hi:[1,0]
	v_add_f32_dpp v230, v230, v230 quad_perm:[1,0,3,2] row_mask:0xf bank_mask:0xf
	v_pk_mul_f32 v[238:239], v[100:101], v[94:95] op_sel:[0,1]
	ds_read_b128 v[96:99], v240 offset:35904
	v_add_f32_dpp v230, v230, v230 quad_perm:[2,3,0,1] row_mask:0xf bank_mask:0xf
	v_pk_fma_f32 v[232:233], v[206:207], v[80:81], v[232:233] op_sel_hi:[1,0,1]
	v_pk_fma_f32 v[234:235], v[208:209], v[80:81], v[234:235] op_sel:[0,1,0]
	v_add_f32_dpp v230, v230, v230 row_half_mirror row_mask:0xf bank_mask:0xf
	v_pk_fma_f32 v[236:237], v[210:211], v[82:83], v[236:237] op_sel_hi:[1,0,1]
	v_pk_fma_f32 v[238:239], v[212:213], v[82:83], v[238:239] op_sel:[0,1,0]
	v_mov_b32_dpp v231, v230 row_ror:8 row_mask:0xf bank_mask:0xf
	ds_write_b64 v217, v[228:229] offset:1152
	v_pk_fma_f32 v[206:207], v[88:89], v[230:231], v[232:233] op_sel_hi:[0,1,1] neg_lo:[1,0,0] neg_hi:[1,0,0]
	v_pk_fma_f32 v[208:209], v[88:89], v[230:231], v[234:235] op_sel:[1,0,0] neg_lo:[1,0,0] neg_hi:[1,0,0]
	v_pk_fma_f32 v[210:211], v[90:91], v[230:231], v[236:237] op_sel_hi:[0,1,1] neg_lo:[1,0,0] neg_hi:[1,0,0]
	v_pk_fma_f32 v[212:213], v[90:91], v[230:231], v[238:239] op_sel:[1,0,0] neg_lo:[1,0,0] neg_hi:[1,0,0]
	s_waitcnt lgkmcnt(8)
	ds_read_b128 v[84:87], v240 offset:10336
	ds_read_b64 v[100:101], v242 offset:45152
	ds_read_b128 v[92:95], v240 offset:27744
	ds_read_b128 v[80:83], v240 offset:1632
	ds_read_b128 v[88:91], v240 offset:19040
	v_pk_mul_f32 v[226:227], v[206:207], v[106:107] op_sel_hi:[1,0]
	v_pk_mul_f32 v[228:229], v[206:207], v[222:223] op_sel_hi:[1,0]
	v_pk_fma_f32 v[226:227], v[208:209], v[106:107], v[226:227] op_sel:[0,1,0]
	v_pk_fma_f32 v[228:229], v[208:209], v[222:223], v[228:229] op_sel:[0,1,0]
	v_pk_fma_f32 v[226:227], v[210:211], v[108:109], v[226:227] op_sel_hi:[1,0,1]
	v_pk_fma_f32 v[228:229], v[210:211], v[224:225], v[228:229] op_sel_hi:[1,0,1]
	v_pk_fma_f32 v[226:227], v[212:213], v[108:109], v[226:227] op_sel:[0,1,0]
	v_pk_fma_f32 v[228:229], v[212:213], v[224:225], v[228:229] op_sel:[0,1,0]
	v_pk_mul_f32 v[232:233], v[118:119], v[114:115] op_sel_hi:[1,0]
	v_add_f32_dpp v230, v227, v226 row_ror:8 row_mask:0xf bank_mask:0xf
	v_pk_mul_f32 v[234:235], v[118:119], v[114:115] op_sel:[0,1]
	v_pk_mul_f32 v[236:237], v[118:119], v[116:117] op_sel_hi:[1,0]
	v_add_f32_dpp v230, v230, v230 quad_perm:[1,0,3,2] row_mask:0xf bank_mask:0xf
	v_pk_mul_f32 v[238:239], v[118:119], v[116:117] op_sel:[0,1]
	ds_read_b128 v[222:225], v240 offset:36176
	v_add_f32_dpp v230, v230, v230 quad_perm:[2,3,0,1] row_mask:0xf bank_mask:0xf
	v_pk_fma_f32 v[232:233], v[206:207], v[102:103], v[232:233] op_sel_hi:[1,0,1]
	v_pk_fma_f32 v[234:235], v[208:209], v[102:103], v[234:235] op_sel:[0,1,0]
	v_add_f32_dpp v230, v230, v230 row_half_mirror row_mask:0xf bank_mask:0xf
	v_pk_fma_f32 v[236:237], v[210:211], v[104:105], v[236:237] op_sel_hi:[1,0,1]
	v_pk_fma_f32 v[238:239], v[212:213], v[104:105], v[238:239] op_sel:[0,1,0]
	v_mov_b32_dpp v231, v230 row_ror:8 row_mask:0xf bank_mask:0xf
	ds_write_b64 v217, v[228:229] offset:1728
	v_pk_fma_f32 v[206:207], v[110:111], v[230:231], v[232:233] op_sel_hi:[0,1,1] neg_lo:[1,0,0] neg_hi:[1,0,0]
	v_pk_fma_f32 v[208:209], v[110:111], v[230:231], v[234:235] op_sel:[1,0,0] neg_lo:[1,0,0] neg_hi:[1,0,0]
	v_pk_fma_f32 v[210:211], v[112:113], v[230:231], v[236:237] op_sel_hi:[0,1,1] neg_lo:[1,0,0] neg_hi:[1,0,0]
	v_pk_fma_f32 v[212:213], v[112:113], v[230:231], v[238:239] op_sel:[1,0,0] neg_lo:[1,0,0] neg_hi:[1,0,0]
	s_waitcnt lgkmcnt(8)
; template <int CTRL> __device__ __forceinline__ float dppf(float x) { return __builtin_bit_cast(float, __builtin_amdgcn_update_dpp(0, __builtin_bit_cast(int, x), CTRL, 0xF, 0xF, false)); }
; __device__ __forceinline__ void phase_rwkv_scan(const Fr& F, int jr) {
;     ...
;                 for (int pg = 0; pg < 64; pg += 16) {
; #pragma unroll
;                     for (int pi = 0; pi < 16; ++pi) {
;                         const int p = pg + pi, pn = p < 63 ? p + 1 : 63;
;                         const f32x4 w4n = PW[pn * 16], k4n = PW[1024 + pn * 16], b4n = PW[2048 + pn * 16], d4n = PW[3072 + pn * 16], r4n = PR[pn * 16];
;                         const float vvn = PV[pn * 32];
;                         f32x2 t = S01 * k4.xy; t = S23 * k4.zw + t; float sa = t.x + t.y;
;                         sa += dppf<0x128>(sa);
;                         const f32x2 dv01 = d4.xy * vv, dv23 = d4.zw * vv;
;                         sa += dppf<0x124>(sa);
;                         const f32x2 e01 = S01 * w4.xy + dv01;
;                         sa += dppf<0x122>(sa);
;                         const f32x2 e23 = S23 * w4.zw + dv23;
;                         sa += dppf<0x121>(sa);
;                         S01 = e01 - b4.xy * sa; S23 = e23 - b4.zw * sa;
;                         f32x2 u = S01 * r4.xy; u = S23 * r4.zw + u;
;                         PY[pi * 64] = u.x + u.y;
;                         w4 = w4n; k4 = k4n; b4 = b4n; d4 = d4n; r4 = r4n; vv = vvn;
;                     }
	ds_read_b128 v[106:109], v240 offset:10608
	ds_read_b64 v[118:119], v242 offset:45424
	ds_read_b128 v[114:117], v240 offset:28016
	ds_read_b128 v[102:105], v240 offset:1904
	ds_read_b128 v[110:113], v240 offset:19312
	v_pk_mul_f32 v[226:227], v[206:207], v[4:5] op_sel_hi:[1,0]
	v_pk_mul_f32 v[228:229], v[206:207], v[96:97] op_sel_hi:[1,0]
	v_pk_fma_f32 v[226:227], v[208:209], v[4:5], v[226:227] op_sel:[0,1,0]
	v_pk_fma_f32 v[228:229], v[208:209], v[96:97], v[228:229] op_sel:[0,1,0]
	v_pk_fma_f32 v[226:227], v[210:211], v[6:7], v[226:227] op_sel_hi:[1,0,1]
	v_pk_fma_f32 v[228:229], v[210:211], v[98:99], v[228:229] op_sel_hi:[1,0,1]
	v_pk_fma_f32 v[226:227], v[212:213], v[6:7], v[226:227] op_sel:[0,1,0]
	v_pk_fma_f32 v[228:229], v[212:213], v[98:99], v[228:229] op_sel:[0,1,0]
	v_pk_mul_f32 v[232:233], v[16:17], v[12:13] op_sel_hi:[1,0]
	v_add_f32_dpp v230, v227, v226 row_ror:8 row_mask:0xf bank_mask:0xf
	v_pk_mul_f32 v[234:235], v[16:17], v[12:13] op_sel:[0,1]
	v_pk_mul_f32 v[236:237], v[16:17], v[14:15] op_sel_hi:[1,0]
	v_add_f32_dpp v230, v230, v230 quad_perm:[1,0,3,2] row_mask:0xf bank_mask:0xf
	v_pk_mul_f32 v[238:239], v[16:17], v[14:15] op_sel:[0,1]
	ds_read_b128 v[96:99], v240 offset:36448
	v_add_f32_dpp v230, v230, v230 quad_perm:[2,3,0,1] row_mask:0xf bank_mask:0xf
	v_pk_fma_f32 v[232:233], v[206:207], v[0:1], v[232:233] op_sel_hi:[1,0,1]
	v_pk_fma_f32 v[234:235], v[208:209], v[0:1], v[234:235] op_sel:[0,1,0]
	v_add_f32_dpp v230, v230, v230 row_half_mirror row_mask:0xf bank_mask:0xf
	v_pk_fma_f32 v[236:237], v[210:211], v[2:3], v[236:237] op_sel_hi:[1,0,1]
	v_pk_fma_f32 v[238:239], v[212:213], v[2:3], v[238:239] op_sel:[0,1,0]
	v_mov_b32_dpp v231, v230 row_ror:8 row_mask:0xf bank_mask:0xf
	ds_write_b64 v217, v[228:229] offset:2304
	v_pk_fma_f32 v[206:207], v[8:9], v[230:231], v[232:233] op_sel_hi:[0,1,1] neg_lo:[1,0,0] neg_hi:[1,0,0]
	v_pk_fma_f32 v[208:209], v[8:9], v[230:231], v[234:235] op_sel:[1,0,0] neg_lo:[1,0,0] neg_hi:[1,0,0]
	v_pk_fma_f32 v[210:211], v[10:11], v[230:231], v[236:237] op_sel_hi:[0,1,1] neg_lo:[1,0,0] neg_hi:[1,0,0]
	v_pk_fma_f32 v[212:213], v[10:11], v[230:231], v[238:239] op_sel:[1,0,0] neg_lo:[1,0,0] neg_hi:[1,0,0]
	s_waitcnt lgkmcnt(8)
	ds_read_b128 v[4:7], v240 offset:10880
	ds_read_b64 v[16:17], v242 offset:45696
	ds_read_b128 v[12:15], v240 offset:28288
	ds_read_b128 v[0:3], v240 offset:2176
	ds_read_b128 v[8:11], v240 offset:19584
	v_pk_mul_f32 v[226:227], v[206:207], v[84:85] op_sel_hi:[1,0]
	v_pk_mul_f32 v[228:229], v[206:207], v[222:223] op_sel_hi:[1,0]
	v_pk_fma_f32 v[226:227], v[208:209], v[84:85], v[226:227] op_sel:[0,1,0]
	v_pk_fma_f32 v[228:229], v[208:209], v[222:223], v[228:229] op_sel:[0,1,0]
	v_pk_fma_f32 v[226:227], v[210:211], v[86:87], v[226:227] op_sel_hi:[1,0,1]
	v_pk_fma_f32 v[228:229], v[210:211], v[224:225], v[228:229] op_sel_hi:[1,0,1]
	v_pk_fma_f32 v[226:227], v[212:213], v[86:87], v[226:227] op_sel:[0,1,0]
	v_pk_fma_f32 v[228:229], v[212:213], v[224:225], v[228:229] op_sel:[0,1,0]
	v_pk_mul_f32 v[232:233], v[100:101], v[92:93] op_sel_hi:[1,0]
	v_add_f32_dpp v230, v227, v226 row_ror:8 row_mask:0xf bank_mask:0xf
	v_pk_mul_f32 v[234:235], v[100:101], v[92:93] op_sel:[0,1]
	v_pk_mul_f32 v[236:237], v[100:101], v[94:95] op_sel_hi:[1,0]
	v_add_f32_dpp v230, v230, v230 quad_perm:[1,0,3,2] row_mask:0xf bank_mask:0xf
	v_pk_mul_f32 v[238:239], v[100:101], v[94:95] op_sel:[0,1]
	ds_read_b128 v[222:225], v240 offset:36720
	v_add_f32_dpp v230, v230, v230 quad_perm:[2,3,0,1] row_mask:0xf bank_mask:0xf
	v_pk_fma_f32 v[232:233], v[206:207], v[80:81], v[232:233] op_sel_hi:[1,0,1]
	v_pk_fma_f32 v[234:235], v[208:209], v[80:81], v[234:235] op_sel:[0,1,0]
	v_add_f32_dpp v230, v230, v230 row_half_mirror row_mask:0xf bank_mask:0xf
	v_pk_fma_f32 v[236:237], v[210:211], v[82:83], v[236:237] op_sel_hi:[1,0,1]
	v_pk_fma_f32 v[238:239], v[212:213], v[82:83], v[238:239] op_sel:[0,1,0]
	v_mov_b32_dpp v231, v230 row_ror:8 row_mask:0xf bank_mask:0xf
	ds_write_b64 v217, v[228:229] offset:2880
	v_pk_fma_f32 v[206:207], v[88:89], v[230:231], v[232:233] op_sel_hi:[0,1,1] neg_lo:[1,0,0] neg_hi:[1,0,0]
	v_pk_fma_f32 v[208:209], v[88:89], v[230:231], v[234:235] op_sel:[1,0,0] neg_lo:[1,0,0] neg_hi:[1,0,0]
	v_pk_fma_f32 v[210:211], v[90:91], v[230:231], v[236:237] op_sel_hi:[0,1,1] neg_lo:[1,0,0] neg_hi:[1,0,0]
	v_pk_fma_f32 v[212:213], v[90:91], v[230:231], v[238:239] op_sel:[1,0,0] neg_lo:[1,0,0] neg_hi:[1,0,0]
	s_waitcnt lgkmcnt(8)
	ds_read_b128 v[84:87], v240 offset:11152
	ds_read_b64 v[100:101], v242 offset:45968
	ds_read_b128 v[92:95], v240 offset:28560
	ds_read_b128 v[80:83], v240 offset:2448
	ds_read_b128 v[88:91], v240 offset:19856
	v_pk_mul_f32 v[226:227], v[206:207], v[106:107] op_sel_hi:[1,0]
	v_pk_mul_f32 v[228:229], v[206:207], v[96:97] op_sel_hi:[1,0]
	v_pk_fma_f32 v[226:227], v[208:209], v[106:107], v[226:227] op_sel:[0,1,0]
	v_pk_fma_f32 v[228:229], v[208:209], v[96:97], v[228:229] op_sel:[0,1,0]
	v_pk_fma_f32 v[226:227], v[210:211], v[108:109], v[226:227] op_sel_hi:[1,0,1]
	v_pk_fma_f32 v[228:229], v[210:211], v[98:99], v[228:229] op_sel_hi:[1,0,1]
	v_pk_fma_f32 v[226:227], v[212:213], v[108:109], v[226:227] op_sel:[0,1,0]
	v_pk_fma_f32 v[228:229], v[212:213], v[98:99], v[228:229] op_sel:[0,1,0]
	v_pk_mul_f32 v[232:233], v[118:119], v[114:115] op_sel_hi:[1,0]
	v_add_f32_dpp v230, v227, v226 row_ror:8 row_mask:0xf bank_mask:0xf
	v_pk_mul_f32 v[234:235], v[118:119], v[114:115] op_sel:[0,1]
	v_pk_mul_f32 v[236:237], v[118:119], v[116:117] op_sel_hi:[1,0]
	v_add_f32_dpp v230, v230, v230 quad_perm:[1,0,3,2] row_mask:0xf bank_mask:0xf
	v_pk_mul_f32 v[238:239], v[118:119], v[116:117] op_sel:[0,1]
	ds_read_b128 v[96:99], v240 offset:36992
	v_add_f32_dpp v230, v230, v230 quad_perm:[2,3,0,1] row_mask:0xf bank_mask:0xf
	v_pk_fma_f32 v[232:233], v[206:207], v[102:103], v[232:233] op_sel_hi:[1,0,1]
	v_pk_fma_f32 v[234:235], v[208:209], v[102:103], v[234:235] op_sel:[0,1,0]
	v_add_f32_dpp v230, v230, v230 row_half_mirror row_mask:0xf bank_mask:0xf
	v_pk_fma_f32 v[236:237], v[210:211], v[104:105], v[236:237] op_sel_hi:[1,0,1]
	v_pk_fma_f32 v[238:239], v[212:213], v[104:105], v[238:239] op_sel:[0,1,0]
	v_mov_b32_dpp v231, v230 row_ror:8 row_mask:0xf bank_mask:0xf
	ds_write_b64 v217, v[228:229] offset:3456
	v_pk_fma_f32 v[206:207], v[110:111], v[230:231], v[232:233] op_sel_hi:[0,1,1] neg_lo:[1,0,0] neg_hi:[1,0,0]
	v_pk_fma_f32 v[208:209], v[110:111], v[230:231], v[234:235] op_sel:[1,0,0] neg_lo:[1,0,0] neg_hi:[1,0,0]
	v_pk_fma_f32 v[210:211], v[112:113], v[230:231], v[236:237] op_sel_hi:[0,1,1] neg_lo:[1,0,0] neg_hi:[1,0,0]
	v_pk_fma_f32 v[212:213], v[112:113], v[230:231], v[238:239] op_sel:[1,0,0] neg_lo:[1,0,0] neg_hi:[1,0,0]
	s_waitcnt lgkmcnt(8)
; template <int CTRL> __device__ __forceinline__ float dppf(float x) { return __builtin_bit_cast(float, __builtin_amdgcn_update_dpp(0, __builtin_bit_cast(int, x), CTRL, 0xF, 0xF, false)); }
; __device__ __forceinline__ void phase_rwkv_scan(const Fr& F, int jr) {
;     ...
;                 for (int pg = 0; pg < 64; pg += 16) {
; #pragma unroll
;                     for (int pi = 0; pi < 16; ++pi) {
;                         const int p = pg + pi, pn = p < 63 ? p + 1 : 63;
;                         const f32x4 w4n = PW[pn * 16], k4n = PW[1024 + pn * 16], b4n = PW[2048 + pn * 16], d4n = PW[3072 + pn * 16], r4n = PR[pn * 16];
;                         const float vvn = PV[pn * 32];
;                         f32x2 t = S01 * k4.xy; t = S23 * k4.zw + t; float sa = t.x + t.y;
;                         sa += dppf<0x128>(sa);
;                         const f32x2 dv01 = d4.xy * vv, dv23 = d4.zw * vv;
;                         sa += dppf<0x124>(sa);
;                         const f32x2 e01 = S01 * w4.xy + dv01;
;                         sa += dppf<0x122>(sa);
;                         const f32x2 e23 = S23 * w4.zw + dv23;
;                         sa += dppf<0x121>(sa);
;                         S01 = e01 - b4.xy * sa; S23 = e23 - b4.zw * sa;
;                         f32x2 u = S01 * r4.xy; u = S23 * r4.zw + u;
;                         PY[pi * 64] = u.x + u.y;
;                         w4 = w4n; k4 = k4n; b4 = b4n; d4 = d4n; r4 = r4n; vv = vvn;
;                     }
	ds_read_b128 v[106:109], v240 offset:11424
	ds_read_b64 v[118:119], v242 offset:46240
	ds_read_b128 v[114:117], v240 offset:28832
	ds_read_b128 v[102:105], v240 offset:2720
	ds_read_b128 v[110:113], v240 offset:20128
	v_pk_mul_f32 v[226:227], v[206:207], v[4:5] op_sel_hi:[1,0]
	v_pk_mul_f32 v[228:229], v[206:207], v[222:223] op_sel_hi:[1,0]
	v_pk_fma_f32 v[226:227], v[208:209], v[4:5], v[226:227] op_sel:[0,1,0]
	v_pk_fma_f32 v[228:229], v[208:209], v[222:223], v[228:229] op_sel:[0,1,0]
	v_pk_fma_f32 v[226:227], v[210:211], v[6:7], v[226:227] op_sel_hi:[1,0,1]
	v_pk_fma_f32 v[228:229], v[210:211], v[224:225], v[228:229] op_sel_hi:[1,0,1]
	v_pk_fma_f32 v[226:227], v[212:213], v[6:7], v[226:227] op_sel:[0,1,0]
	v_pk_fma_f32 v[228:229], v[212:213], v[224:225], v[228:229] op_sel:[0,1,0]
	v_pk_mul_f32 v[232:233], v[16:17], v[12:13] op_sel_hi:[1,0]
	v_add_f32_dpp v230, v227, v226 row_ror:8 row_mask:0xf bank_mask:0xf
	v_pk_mul_f32 v[234:235], v[16:17], v[12:13] op_sel:[0,1]
	v_pk_mul_f32 v[236:237], v[16:17], v[14:15] op_sel_hi:[1,0]
	v_add_f32_dpp v230, v230, v230 quad_perm:[1,0,3,2] row_mask:0xf bank_mask:0xf
	v_pk_mul_f32 v[238:239], v[16:17], v[14:15] op_sel:[0,1]
	ds_read_b128 v[222:225], v240 offset:37264
	v_add_f32_dpp v230, v230, v230 quad_perm:[2,3,0,1] row_mask:0xf bank_mask:0xf
	v_pk_fma_f32 v[232:233], v[206:207], v[0:1], v[232:233] op_sel_hi:[1,0,1]
	v_pk_fma_f32 v[234:235], v[208:209], v[0:1], v[234:235] op_sel:[0,1,0]
	v_add_f32_dpp v230, v230, v230 row_half_mirror row_mask:0xf bank_mask:0xf
	v_pk_fma_f32 v[236:237], v[210:211], v[2:3], v[236:237] op_sel_hi:[1,0,1]
	v_pk_fma_f32 v[238:239], v[212:213], v[2:3], v[238:239] op_sel:[0,1,0]
	v_mov_b32_dpp v231, v230 row_ror:8 row_mask:0xf bank_mask:0xf
	ds_write_b64 v217, v[228:229] offset:4032
	v_pk_fma_f32 v[206:207], v[8:9], v[230:231], v[232:233] op_sel_hi:[0,1,1] neg_lo:[1,0,0] neg_hi:[1,0,0]
	v_pk_fma_f32 v[208:209], v[8:9], v[230:231], v[234:235] op_sel:[1,0,0] neg_lo:[1,0,0] neg_hi:[1,0,0]
	v_pk_fma_f32 v[210:211], v[10:11], v[230:231], v[236:237] op_sel_hi:[0,1,1] neg_lo:[1,0,0] neg_hi:[1,0,0]
	v_pk_fma_f32 v[212:213], v[10:11], v[230:231], v[238:239] op_sel:[1,0,0] neg_lo:[1,0,0] neg_hi:[1,0,0]
	s_waitcnt lgkmcnt(8)
	ds_read_b128 v[4:7], v240 offset:11696
	ds_read_b64 v[16:17], v242 offset:46512
	ds_read_b128 v[12:15], v240 offset:29104
	ds_read_b128 v[0:3], v240 offset:2992
	ds_read_b128 v[8:11], v240 offset:20400
	v_pk_mul_f32 v[226:227], v[206:207], v[84:85] op_sel_hi:[1,0]
	v_pk_mul_f32 v[228:229], v[206:207], v[96:97] op_sel_hi:[1,0]
	v_pk_fma_f32 v[226:227], v[208:209], v[84:85], v[226:227] op_sel:[0,1,0]
	v_pk_fma_f32 v[228:229], v[208:209], v[96:97], v[228:229] op_sel:[0,1,0]
	v_pk_fma_f32 v[226:227], v[210:211], v[86:87], v[226:227] op_sel_hi:[1,0,1]
	v_pk_fma_f32 v[228:229], v[210:211], v[98:99], v[228:229] op_sel_hi:[1,0,1]
	v_pk_fma_f32 v[226:227], v[212:213], v[86:87], v[226:227] op_sel:[0,1,0]
	v_pk_fma_f32 v[228:229], v[212:213], v[98:99], v[228:229] op_sel:[0,1,0]
	v_pk_mul_f32 v[232:233], v[100:101], v[92:93] op_sel_hi:[1,0]
	v_add_f32_dpp v230, v227, v226 row_ror:8 row_mask:0xf bank_mask:0xf
	v_pk_mul_f32 v[234:235], v[100:101], v[92:93] op_sel:[0,1]
	v_pk_mul_f32 v[236:237], v[100:101], v[94:95] op_sel_hi:[1,0]
	v_add_f32_dpp v230, v230, v230 quad_perm:[1,0,3,2] row_mask:0xf bank_mask:0xf
	v_pk_mul_f32 v[238:239], v[100:101], v[94:95] op_sel:[0,1]
	ds_read_b128 v[96:99], v240 offset:37536
	v_add_f32_dpp v230, v230, v230 quad_perm:[2,3,0,1] row_mask:0xf bank_mask:0xf
	v_pk_fma_f32 v[232:233], v[206:207], v[80:81], v[232:233] op_sel_hi:[1,0,1]
	v_pk_fma_f32 v[234:235], v[208:209], v[80:81], v[234:235] op_sel:[0,1,0]
	v_add_f32_dpp v230, v230, v230 row_half_mirror row_mask:0xf bank_mask:0xf
	v_pk_fma_f32 v[236:237], v[210:211], v[82:83], v[236:237] op_sel_hi:[1,0,1]
	v_pk_fma_f32 v[238:239], v[212:213], v[82:83], v[238:239] op_sel:[0,1,0]
	v_mov_b32_dpp v231, v230 row_ror:8 row_mask:0xf bank_mask:0xf
	ds_write_b64 v217, v[228:229] offset:4608
	v_pk_fma_f32 v[206:207], v[88:89], v[230:231], v[232:233] op_sel_hi:[0,1,1] neg_lo:[1,0,0] neg_hi:[1,0,0]
	v_pk_fma_f32 v[208:209], v[88:89], v[230:231], v[234:235] op_sel:[1,0,0] neg_lo:[1,0,0] neg_hi:[1,0,0]
	v_pk_fma_f32 v[210:211], v[90:91], v[230:231], v[236:237] op_sel_hi:[0,1,1] neg_lo:[1,0,0] neg_hi:[1,0,0]
	v_pk_fma_f32 v[212:213], v[90:91], v[230:231], v[238:239] op_sel:[1,0,0] neg_lo:[1,0,0] neg_hi:[1,0,0]
	s_waitcnt lgkmcnt(8)
	ds_read_b128 v[84:87], v240 offset:11968
	ds_read_b64 v[100:101], v242 offset:46784
	ds_read_b128 v[92:95], v240 offset:29376
	ds_read_b128 v[80:83], v240 offset:3264
	ds_read_b128 v[88:91], v240 offset:20672
	v_pk_mul_f32 v[226:227], v[206:207], v[106:107] op_sel_hi:[1,0]
	v_pk_mul_f32 v[228:229], v[206:207], v[222:223] op_sel_hi:[1,0]
	v_pk_fma_f32 v[226:227], v[208:209], v[106:107], v[226:227] op_sel:[0,1,0]
	v_pk_fma_f32 v[228:229], v[208:209], v[222:223], v[228:229] op_sel:[0,1,0]
	v_pk_fma_f32 v[226:227], v[210:211], v[108:109], v[226:227] op_sel_hi:[1,0,1]
	v_pk_fma_f32 v[228:229], v[210:211], v[224:225], v[228:229] op_sel_hi:[1,0,1]
	v_pk_fma_f32 v[226:227], v[212:213], v[108:109], v[226:227] op_sel:[0,1,0]
	v_pk_fma_f32 v[228:229], v[212:213], v[224:225], v[228:229] op_sel:[0,1,0]
	v_pk_mul_f32 v[232:233], v[118:119], v[114:115] op_sel_hi:[1,0]
	v_add_f32_dpp v230, v227, v226 row_ror:8 row_mask:0xf bank_mask:0xf
	v_pk_mul_f32 v[234:235], v[118:119], v[114:115] op_sel:[0,1]
	v_pk_mul_f32 v[236:237], v[118:119], v[116:117] op_sel_hi:[1,0]
	v_add_f32_dpp v230, v230, v230 quad_perm:[1,0,3,2] row_mask:0xf bank_mask:0xf
	v_pk_mul_f32 v[238:239], v[118:119], v[116:117] op_sel:[0,1]
	ds_read_b128 v[222:225], v240 offset:37808
	v_add_f32_dpp v230, v230, v230 quad_perm:[2,3,0,1] row_mask:0xf bank_mask:0xf
	v_pk_fma_f32 v[232:233], v[206:207], v[102:103], v[232:233] op_sel_hi:[1,0,1]
	v_pk_fma_f32 v[234:235], v[208:209], v[102:103], v[234:235] op_sel:[0,1,0]
	v_add_f32_dpp v230, v230, v230 row_half_mirror row_mask:0xf bank_mask:0xf
	v_pk_fma_f32 v[236:237], v[210:211], v[104:105], v[236:237] op_sel_hi:[1,0,1]
	v_pk_fma_f32 v[238:239], v[212:213], v[104:105], v[238:239] op_sel:[0,1,0]
	v_mov_b32_dpp v231, v230 row_ror:8 row_mask:0xf bank_mask:0xf
	ds_write_b64 v217, v[228:229] offset:5184
	v_pk_fma_f32 v[206:207], v[110:111], v[230:231], v[232:233] op_sel_hi:[0,1,1] neg_lo:[1,0,0] neg_hi:[1,0,0]
	v_pk_fma_f32 v[208:209], v[110:111], v[230:231], v[234:235] op_sel:[1,0,0] neg_lo:[1,0,0] neg_hi:[1,0,0]
	v_pk_fma_f32 v[210:211], v[112:113], v[230:231], v[236:237] op_sel_hi:[0,1,1] neg_lo:[1,0,0] neg_hi:[1,0,0]
	v_pk_fma_f32 v[212:213], v[112:113], v[230:231], v[238:239] op_sel:[1,0,0] neg_lo:[1,0,0] neg_hi:[1,0,0]
	s_waitcnt lgkmcnt(8)
; template <int CTRL> __device__ __forceinline__ float dppf(float x) { return __builtin_bit_cast(float, __builtin_amdgcn_update_dpp(0, __builtin_bit_cast(int, x), CTRL, 0xF, 0xF, false)); }
; __device__ __forceinline__ void phase_rwkv_scan(const Fr& F, int jr) {
;     ...
;                 for (int pg = 0; pg < 64; pg += 16) {
; #pragma unroll
;                     for (int pi = 0; pi < 16; ++pi) {
;                         const int p = pg + pi, pn = p < 63 ? p + 1 : 63;
;                         const f32x4 w4n = PW[pn * 16], k4n = PW[1024 + pn * 16], b4n = PW[2048 + pn * 16], d4n = PW[3072 + pn * 16], r4n = PR[pn * 16];
;                         const float vvn = PV[pn * 32];
;                         f32x2 t = S01 * k4.xy; t = S23 * k4.zw + t; float sa = t.x + t.y;
;                         sa += dppf<0x128>(sa);
;                         const f32x2 dv01 = d4.xy * vv, dv23 = d4.zw * vv;
;                         sa += dppf<0x124>(sa);
;                         const f32x2 e01 = S01 * w4.xy + dv01;
;                         sa += dppf<0x122>(sa);
;                         const f32x2 e23 = S23 * w4.zw + dv23;
;                         sa += dppf<0x121>(sa);
;                         S01 = e01 - b4.xy * sa; S23 = e23 - b4.zw * sa;
;                         f32x2 u = S01 * r4.xy; u = S23 * r4.zw + u;
;                         PY[pi * 64] = u.x + u.y;
;                         w4 = w4n; k4 = k4n; b4 = b4n; d4 = d4n; r4 = r4n; vv = vvn;
;                     }
	ds_read_b128 v[106:109], v240 offset:12240
	ds_read_b64 v[118:119], v242 offset:47056
	ds_read_b128 v[114:117], v240 offset:29648
	ds_read_b128 v[102:105], v240 offset:3536
	ds_read_b128 v[110:113], v240 offset:20944
	v_pk_mul_f32 v[226:227], v[206:207], v[4:5] op_sel_hi:[1,0]
	v_pk_mul_f32 v[228:229], v[206:207], v[96:97] op_sel_hi:[1,0]
	v_pk_fma_f32 v[226:227], v[208:209], v[4:5], v[226:227] op_sel:[0,1,0]
	v_pk_fma_f32 v[228:229], v[208:209], v[96:97], v[228:229] op_sel:[0,1,0]
	v_pk_fma_f32 v[226:227], v[210:211], v[6:7], v[226:227] op_sel_hi:[1,0,1]
	v_pk_fma_f32 v[228:229], v[210:211], v[98:99], v[228:229] op_sel_hi:[1,0,1]
	v_pk_fma_f32 v[226:227], v[212:213], v[6:7], v[226:227] op_sel:[0,1,0]
	v_pk_fma_f32 v[228:229], v[212:213], v[98:99], v[228:229] op_sel:[0,1,0]
	v_pk_mul_f32 v[232:233], v[16:17], v[12:13] op_sel_hi:[1,0]
	v_add_f32_dpp v230, v227, v226 row_ror:8 row_mask:0xf bank_mask:0xf
	v_pk_mul_f32 v[234:235], v[16:17], v[12:13] op_sel:[0,1]
	v_pk_mul_f32 v[236:237], v[16:17], v[14:15] op_sel_hi:[1,0]
	v_add_f32_dpp v230, v230, v230 quad_perm:[1,0,3,2] row_mask:0xf bank_mask:0xf
	v_pk_mul_f32 v[238:239], v[16:17], v[14:15] op_sel:[0,1]
	ds_read_b128 v[96:99], v240 offset:38080
	v_add_f32_dpp v230, v230, v230 quad_perm:[2,3,0,1] row_mask:0xf bank_mask:0xf
	v_pk_fma_f32 v[232:233], v[206:207], v[0:1], v[232:233] op_sel_hi:[1,0,1]
	v_pk_fma_f32 v[234:235], v[208:209], v[0:1], v[234:235] op_sel:[0,1,0]
	v_add_f32_dpp v230, v230, v230 row_half_mirror row_mask:0xf bank_mask:0xf
	v_pk_fma_f32 v[236:237], v[210:211], v[2:3], v[236:237] op_sel_hi:[1,0,1]
	v_pk_fma_f32 v[238:239], v[212:213], v[2:3], v[238:239] op_sel:[0,1,0]
	v_mov_b32_dpp v231, v230 row_ror:8 row_mask:0xf bank_mask:0xf
	ds_write_b64 v217, v[228:229] offset:5760
	v_pk_fma_f32 v[206:207], v[8:9], v[230:231], v[232:233] op_sel_hi:[0,1,1] neg_lo:[1,0,0] neg_hi:[1,0,0]
	v_pk_fma_f32 v[208:209], v[8:9], v[230:231], v[234:235] op_sel:[1,0,0] neg_lo:[1,0,0] neg_hi:[1,0,0]
	v_pk_fma_f32 v[210:211], v[10:11], v[230:231], v[236:237] op_sel_hi:[0,1,1] neg_lo:[1,0,0] neg_hi:[1,0,0]
	v_pk_fma_f32 v[212:213], v[10:11], v[230:231], v[238:239] op_sel:[1,0,0] neg_lo:[1,0,0] neg_hi:[1,0,0]
	s_waitcnt lgkmcnt(8)
	ds_read_b128 v[4:7], v240 offset:12512
	ds_read_b64 v[16:17], v242 offset:47328
	ds_read_b128 v[12:15], v240 offset:29920
	ds_read_b128 v[0:3], v240 offset:3808
	ds_read_b128 v[8:11], v240 offset:21216
	v_pk_mul_f32 v[226:227], v[206:207], v[84:85] op_sel_hi:[1,0]
	v_pk_mul_f32 v[228:229], v[206:207], v[222:223] op_sel_hi:[1,0]
	v_pk_fma_f32 v[226:227], v[208:209], v[84:85], v[226:227] op_sel:[0,1,0]
	v_pk_fma_f32 v[228:229], v[208:209], v[222:223], v[228:229] op_sel:[0,1,0]
	v_pk_fma_f32 v[226:227], v[210:211], v[86:87], v[226:227] op_sel_hi:[1,0,1]
	v_pk_fma_f32 v[228:229], v[210:211], v[224:225], v[228:229] op_sel_hi:[1,0,1]
	v_pk_fma_f32 v[226:227], v[212:213], v[86:87], v[226:227] op_sel:[0,1,0]
	v_pk_fma_f32 v[228:229], v[212:213], v[224:225], v[228:229] op_sel:[0,1,0]
	v_pk_mul_f32 v[232:233], v[100:101], v[92:93] op_sel_hi:[1,0]
	v_add_f32_dpp v230, v227, v226 row_ror:8 row_mask:0xf bank_mask:0xf
	v_pk_mul_f32 v[234:235], v[100:101], v[92:93] op_sel:[0,1]
	v_pk_mul_f32 v[236:237], v[100:101], v[94:95] op_sel_hi:[1,0]
	v_add_f32_dpp v230, v230, v230 quad_perm:[1,0,3,2] row_mask:0xf bank_mask:0xf
	v_pk_mul_f32 v[238:239], v[100:101], v[94:95] op_sel:[0,1]
	ds_read_b128 v[222:225], v240 offset:38352
	v_add_f32_dpp v230, v230, v230 quad_perm:[2,3,0,1] row_mask:0xf bank_mask:0xf
	v_pk_fma_f32 v[232:233], v[206:207], v[80:81], v[232:233] op_sel_hi:[1,0,1]
	v_pk_fma_f32 v[234:235], v[208:209], v[80:81], v[234:235] op_sel:[0,1,0]
	v_add_f32_dpp v230, v230, v230 row_half_mirror row_mask:0xf bank_mask:0xf
	v_pk_fma_f32 v[236:237], v[210:211], v[82:83], v[236:237] op_sel_hi:[1,0,1]
	v_pk_fma_f32 v[238:239], v[212:213], v[82:83], v[238:239] op_sel:[0,1,0]
	v_mov_b32_dpp v231, v230 row_ror:8 row_mask:0xf bank_mask:0xf
	ds_write_b64 v217, v[228:229] offset:6336
	v_pk_fma_f32 v[206:207], v[88:89], v[230:231], v[232:233] op_sel_hi:[0,1,1] neg_lo:[1,0,0] neg_hi:[1,0,0]
	v_pk_fma_f32 v[208:209], v[88:89], v[230:231], v[234:235] op_sel:[1,0,0] neg_lo:[1,0,0] neg_hi:[1,0,0]
	v_pk_fma_f32 v[210:211], v[90:91], v[230:231], v[236:237] op_sel_hi:[0,1,1] neg_lo:[1,0,0] neg_hi:[1,0,0]
	v_pk_fma_f32 v[212:213], v[90:91], v[230:231], v[238:239] op_sel:[1,0,0] neg_lo:[1,0,0] neg_hi:[1,0,0]
	s_waitcnt lgkmcnt(8)
	ds_read_b128 v[84:87], v240 offset:12784
	ds_read_b64 v[100:101], v242 offset:47600
	ds_read_b128 v[92:95], v240 offset:30192
	ds_read_b128 v[80:83], v240 offset:4080
	ds_read_b128 v[88:91], v240 offset:21488
	v_pk_mul_f32 v[226:227], v[206:207], v[106:107] op_sel_hi:[1,0]
	v_pk_mul_f32 v[228:229], v[206:207], v[96:97] op_sel_hi:[1,0]
	v_pk_fma_f32 v[226:227], v[208:209], v[106:107], v[226:227] op_sel:[0,1,0]
	v_pk_fma_f32 v[228:229], v[208:209], v[96:97], v[228:229] op_sel:[0,1,0]
	v_pk_fma_f32 v[226:227], v[210:211], v[108:109], v[226:227] op_sel_hi:[1,0,1]
	v_pk_fma_f32 v[228:229], v[210:211], v[98:99], v[228:229] op_sel_hi:[1,0,1]
	v_pk_fma_f32 v[226:227], v[212:213], v[108:109], v[226:227] op_sel:[0,1,0]
	v_pk_fma_f32 v[228:229], v[212:213], v[98:99], v[228:229] op_sel:[0,1,0]
	v_pk_mul_f32 v[232:233], v[118:119], v[114:115] op_sel_hi:[1,0]
	v_add_f32_dpp v230, v227, v226 row_ror:8 row_mask:0xf bank_mask:0xf
	v_pk_mul_f32 v[234:235], v[118:119], v[114:115] op_sel:[0,1]
	v_pk_mul_f32 v[236:237], v[118:119], v[116:117] op_sel_hi:[1,0]
	v_add_f32_dpp v230, v230, v230 quad_perm:[1,0,3,2] row_mask:0xf bank_mask:0xf
	v_pk_mul_f32 v[238:239], v[118:119], v[116:117] op_sel:[0,1]
	ds_read_b128 v[96:99], v240 offset:38624
	v_add_f32_dpp v230, v230, v230 quad_perm:[2,3,0,1] row_mask:0xf bank_mask:0xf
	v_pk_fma_f32 v[232:233], v[206:207], v[102:103], v[232:233] op_sel_hi:[1,0,1]
	v_pk_fma_f32 v[234:235], v[208:209], v[102:103], v[234:235] op_sel:[0,1,0]
	v_add_f32_dpp v230, v230, v230 row_half_mirror row_mask:0xf bank_mask:0xf
	v_pk_fma_f32 v[236:237], v[210:211], v[104:105], v[236:237] op_sel_hi:[1,0,1]
	v_pk_fma_f32 v[238:239], v[212:213], v[104:105], v[238:239] op_sel:[0,1,0]
	v_mov_b32_dpp v231, v230 row_ror:8 row_mask:0xf bank_mask:0xf
	ds_write_b64 v217, v[228:229] offset:6912
	v_pk_fma_f32 v[206:207], v[110:111], v[230:231], v[232:233] op_sel_hi:[0,1,1] neg_lo:[1,0,0] neg_hi:[1,0,0]
	v_pk_fma_f32 v[208:209], v[110:111], v[230:231], v[234:235] op_sel:[1,0,0] neg_lo:[1,0,0] neg_hi:[1,0,0]
	v_pk_fma_f32 v[210:211], v[112:113], v[230:231], v[236:237] op_sel_hi:[0,1,1] neg_lo:[1,0,0] neg_hi:[1,0,0]
	v_pk_fma_f32 v[212:213], v[112:113], v[230:231], v[238:239] op_sel:[1,0,0] neg_lo:[1,0,0] neg_hi:[1,0,0]
	s_waitcnt lgkmcnt(8)
; __device__ __forceinline__ unsigned f2bf(float f) { unsigned u = __builtin_bit_cast(unsigned, f); return (u + 0x7fffu + ((u >> 16) & 1u)) >> 16; }
; template <int CTRL> __device__ __forceinline__ float dppf(float x) { return __builtin_bit_cast(float, __builtin_amdgcn_update_dpp(0, __builtin_bit_cast(int, x), CTRL, 0xF, 0xF, false)); }
; __device__ __forceinline__ void phase_rwkv_scan(const Fr& F, int jr) {
;     ...
;                 for (int pg = 0; pg < 64; pg += 16) {
; #pragma unroll
;                     for (int pi = 0; pi < 16; ++pi) {
;                         const int p = pg + pi, pn = p < 63 ? p + 1 : 63;
;                         const f32x4 w4n = PW[pn * 16], k4n = PW[1024 + pn * 16], b4n = PW[2048 + pn * 16], d4n = PW[3072 + pn * 16], r4n = PR[pn * 16];
;                         const float vvn = PV[pn * 32];
;                         f32x2 t = S01 * k4.xy; t = S23 * k4.zw + t; float sa = t.x + t.y;
;                         sa += dppf<0x128>(sa);
;                         const f32x2 dv01 = d4.xy * vv, dv23 = d4.zw * vv;
;                         sa += dppf<0x124>(sa);
;                         const f32x2 e01 = S01 * w4.xy + dv01;
;                         sa += dppf<0x122>(sa);
;                         const f32x2 e23 = S23 * w4.zw + dv23;
;                         sa += dppf<0x121>(sa);
;                         S01 = e01 - b4.xy * sa; S23 = e23 - b4.zw * sa;
;                         f32x2 u = S01 * r4.xy; u = S23 * r4.zw + u;
;                         PY[pi * 64] = u.x + u.y;
;                         w4 = w4n; k4 = k4n; b4 = b4n; d4 = d4n; r4 = r4n; vv = vvn;
;                     }
;                     asm volatile("s_waitcnt lgkmcnt(0)" ::: "memory");
;                     {
;                         const int j = lane >> 2, q = lane & 3; const float* yp = Ypw + j * 64 + q * 16;
;                         const f32x4 a0 = *(const f32x4*)yp, a1 = *(const f32x4*)(yp + 4), a2 = *(const f32x4*)(yp + 8), a3 = *(const f32x4*)(yp + 12);
;                         const f32x4 ssum = (a0 + a1) + (a2 + a3); const float yv = (ssum.x + ssum.y) + (ssum.z + ssum.w);
;                         const size_t row = (size_t)b * TB + tokof(s, chunk * 64 + pg + j);
;                         Yb[row * D + h * 64 + 32 * half + 4 * wave + q] = (bf16)f2bf(yv);
;                     }
	ds_read_b128 v[106:109], v240 offset:13056
	ds_read_b64 v[118:119], v242 offset:47872
	ds_read_b128 v[114:117], v240 offset:30464
	ds_read_b128 v[102:105], v240 offset:4352
	ds_read_b128 v[110:113], v240 offset:21760
	v_pk_mul_f32 v[226:227], v[206:207], v[4:5] op_sel_hi:[1,0]
	v_pk_mul_f32 v[228:229], v[206:207], v[222:223] op_sel_hi:[1,0]
	v_pk_fma_f32 v[226:227], v[208:209], v[4:5], v[226:227] op_sel:[0,1,0]
	v_pk_fma_f32 v[228:229], v[208:209], v[222:223], v[228:229] op_sel:[0,1,0]
	v_pk_fma_f32 v[226:227], v[210:211], v[6:7], v[226:227] op_sel_hi:[1,0,1]
	v_pk_fma_f32 v[228:229], v[210:211], v[224:225], v[228:229] op_sel_hi:[1,0,1]
	v_pk_fma_f32 v[226:227], v[212:213], v[6:7], v[226:227] op_sel:[0,1,0]
	v_pk_fma_f32 v[228:229], v[212:213], v[224:225], v[228:229] op_sel:[0,1,0]
	v_pk_mul_f32 v[232:233], v[16:17], v[12:13] op_sel_hi:[1,0]
	v_add_f32_dpp v230, v227, v226 row_ror:8 row_mask:0xf bank_mask:0xf
	v_pk_mul_f32 v[234:235], v[16:17], v[12:13] op_sel:[0,1]
	v_pk_mul_f32 v[236:237], v[16:17], v[14:15] op_sel_hi:[1,0]
	v_add_f32_dpp v230, v230, v230 quad_perm:[1,0,3,2] row_mask:0xf bank_mask:0xf
	v_pk_mul_f32 v[238:239], v[16:17], v[14:15] op_sel:[0,1]
	ds_read_b128 v[222:225], v240 offset:38896
	v_add_f32_dpp v230, v230, v230 quad_perm:[2,3,0,1] row_mask:0xf bank_mask:0xf
	v_pk_fma_f32 v[232:233], v[206:207], v[0:1], v[232:233] op_sel_hi:[1,0,1]
	v_pk_fma_f32 v[234:235], v[208:209], v[0:1], v[234:235] op_sel:[0,1,0]
	v_add_f32_dpp v230, v230, v230 row_half_mirror row_mask:0xf bank_mask:0xf
	v_pk_fma_f32 v[236:237], v[210:211], v[2:3], v[236:237] op_sel_hi:[1,0,1]
	v_pk_fma_f32 v[238:239], v[212:213], v[2:3], v[238:239] op_sel:[0,1,0]
	v_mov_b32_dpp v231, v230 row_ror:8 row_mask:0xf bank_mask:0xf
	ds_write_b64 v217, v[228:229] offset:7488
	v_pk_fma_f32 v[206:207], v[8:9], v[230:231], v[232:233] op_sel_hi:[0,1,1] neg_lo:[1,0,0] neg_hi:[1,0,0]
	v_pk_fma_f32 v[208:209], v[8:9], v[230:231], v[234:235] op_sel:[1,0,0] neg_lo:[1,0,0] neg_hi:[1,0,0]
	v_pk_fma_f32 v[210:211], v[10:11], v[230:231], v[236:237] op_sel_hi:[0,1,1] neg_lo:[1,0,0] neg_hi:[1,0,0]
	v_pk_fma_f32 v[212:213], v[10:11], v[230:231], v[238:239] op_sel:[1,0,0] neg_lo:[1,0,0] neg_hi:[1,0,0]
	s_waitcnt lgkmcnt(8)
	ds_read_b128 v[4:7], v240 offset:13328
	ds_read_b64 v[16:17], v242 offset:48144
	ds_read_b128 v[12:15], v240 offset:30736
	ds_read_b128 v[0:3], v240 offset:4624
	ds_read_b128 v[8:11], v240 offset:22032
	v_pk_mul_f32 v[226:227], v[206:207], v[84:85] op_sel_hi:[1,0]
	v_pk_mul_f32 v[228:229], v[206:207], v[96:97] op_sel_hi:[1,0]
	v_pk_fma_f32 v[226:227], v[208:209], v[84:85], v[226:227] op_sel:[0,1,0]
	v_pk_fma_f32 v[228:229], v[208:209], v[96:97], v[228:229] op_sel:[0,1,0]
	v_pk_fma_f32 v[226:227], v[210:211], v[86:87], v[226:227] op_sel_hi:[1,0,1]
	v_pk_fma_f32 v[228:229], v[210:211], v[98:99], v[228:229] op_sel_hi:[1,0,1]
	v_pk_fma_f32 v[226:227], v[212:213], v[86:87], v[226:227] op_sel:[0,1,0]
	v_pk_fma_f32 v[228:229], v[212:213], v[98:99], v[228:229] op_sel:[0,1,0]
	v_pk_mul_f32 v[232:233], v[100:101], v[92:93] op_sel_hi:[1,0]
	v_add_f32_dpp v230, v227, v226 row_ror:8 row_mask:0xf bank_mask:0xf
	v_pk_mul_f32 v[234:235], v[100:101], v[92:93] op_sel:[0,1]
	v_pk_mul_f32 v[236:237], v[100:101], v[94:95] op_sel_hi:[1,0]
	v_add_f32_dpp v230, v230, v230 quad_perm:[1,0,3,2] row_mask:0xf bank_mask:0xf
	v_pk_mul_f32 v[238:239], v[100:101], v[94:95] op_sel:[0,1]
	ds_read_b128 v[96:99], v240 offset:39168
	v_add_f32_dpp v230, v230, v230 quad_perm:[2,3,0,1] row_mask:0xf bank_mask:0xf
	v_pk_fma_f32 v[232:233], v[206:207], v[80:81], v[232:233] op_sel_hi:[1,0,1]
	v_pk_fma_f32 v[234:235], v[208:209], v[80:81], v[234:235] op_sel:[0,1,0]
	v_add_f32_dpp v230, v230, v230 row_half_mirror row_mask:0xf bank_mask:0xf
	v_pk_fma_f32 v[236:237], v[210:211], v[82:83], v[236:237] op_sel_hi:[1,0,1]
	v_pk_fma_f32 v[238:239], v[212:213], v[82:83], v[238:239] op_sel:[0,1,0]
	v_mov_b32_dpp v231, v230 row_ror:8 row_mask:0xf bank_mask:0xf
	ds_write_b64 v217, v[228:229] offset:8064
	v_pk_fma_f32 v[206:207], v[88:89], v[230:231], v[232:233] op_sel_hi:[0,1,1] neg_lo:[1,0,0] neg_hi:[1,0,0]
	v_pk_fma_f32 v[208:209], v[88:89], v[230:231], v[234:235] op_sel:[1,0,0] neg_lo:[1,0,0] neg_hi:[1,0,0]
	v_pk_fma_f32 v[210:211], v[90:91], v[230:231], v[236:237] op_sel_hi:[0,1,1] neg_lo:[1,0,0] neg_hi:[1,0,0]
	v_pk_fma_f32 v[212:213], v[90:91], v[230:231], v[238:239] op_sel:[1,0,0] neg_lo:[1,0,0] neg_hi:[1,0,0]
	s_waitcnt lgkmcnt(8)
	v_pk_mul_f32 v[228:229], v[206:207], v[222:223] op_sel_hi:[1,0]
	v_add_u32_e32 v243, s15, v219
	v_pk_fma_f32 v[228:229], v[208:209], v[222:223], v[228:229] op_sel:[0,1,0]
	v_lshl_add_u32 v243, v243, 11, v220
	v_pk_fma_f32 v[228:229], v[210:211], v[224:225], v[228:229] op_sel_hi:[1,0,1]
	s_nop 0
	v_pk_fma_f32 v[228:229], v[212:213], v[224:225], v[228:229] op_sel:[0,1,0]
	s_nop 0
	s_waitcnt lgkmcnt(7)
	ds_write_b64 v217, v[228:229] offset:8640
	ds_read_b128 v[24:27], v218 offset:0
	ds_read_b128 v[28:31], v218 offset:16
	ds_read_b128 v[32:35], v218 offset:32
	ds_read_b128 v[36:39], v218 offset:48
	ds_read_b128 v[40:43], v218 offset:64
	ds_read_b128 v[44:47], v218 offset:80
	ds_read_b128 v[48:51], v218 offset:96
	s_waitcnt lgkmcnt(5)
	ds_read_b128 v[52:55], v218 offset:112
	v_pk_add_f32 v[24:25], v[24:25], v[26:27]
	v_pk_add_f32 v[28:29], v[28:29], v[30:31]
	s_waitcnt lgkmcnt(4)
	v_pk_add_f32 v[32:33], v[32:33], v[34:35]
	v_pk_add_f32 v[36:37], v[36:37], v[38:39]
	v_pk_add_f32 v[24:25], v[24:25], v[28:29]
	s_waitcnt lgkmcnt(2)
	v_pk_add_f32 v[40:41], v[40:41], v[42:43]
	v_pk_add_f32 v[44:45], v[44:45], v[46:47]
	v_pk_add_f32 v[32:33], v[32:33], v[36:37]
	s_waitcnt lgkmcnt(0)
; __device__ __forceinline__ unsigned f2bf(float f) { unsigned u = __builtin_bit_cast(unsigned, f); return (u + 0x7fffu + ((u >> 16) & 1u)) >> 16; }
; template <int CTRL> __device__ __forceinline__ float dppf(float x) { return __builtin_bit_cast(float, __builtin_amdgcn_update_dpp(0, __builtin_bit_cast(int, x), CTRL, 0xF, 0xF, false)); }
; __device__ __forceinline__ void phase_rwkv_scan(const Fr& F, int jr) {
;     ...
;                 for (int pg = 0; pg < 64; pg += 16) {
; #pragma unroll
;                     for (int pi = 0; pi < 16; ++pi) {
;                         const int p = pg + pi, pn = p < 63 ? p + 1 : 63;
;                         const f32x4 w4n = PW[pn * 16], k4n = PW[1024 + pn * 16], b4n = PW[2048 + pn * 16], d4n = PW[3072 + pn * 16], r4n = PR[pn * 16];
;                         const float vvn = PV[pn * 32];
;                         f32x2 t = S01 * k4.xy; t = S23 * k4.zw + t; float sa = t.x + t.y;
;                         sa += dppf<0x128>(sa);
;                         const f32x2 dv01 = d4.xy * vv, dv23 = d4.zw * vv;
;                         sa += dppf<0x124>(sa);
;                         const f32x2 e01 = S01 * w4.xy + dv01;
;                         sa += dppf<0x122>(sa);
;                         const f32x2 e23 = S23 * w4.zw + dv23;
;                         sa += dppf<0x121>(sa);
;                         S01 = e01 - b4.xy * sa; S23 = e23 - b4.zw * sa;
;                         f32x2 u = S01 * r4.xy; u = S23 * r4.zw + u;
;                         PY[pi * 64] = u.x + u.y;
;                         w4 = w4n; k4 = k4n; b4 = b4n; d4 = d4n; r4 = r4n; vv = vvn;
;                     }
;                     asm volatile("s_waitcnt lgkmcnt(0)" ::: "memory");
;                     {
;                         const int j = lane >> 2, q = lane & 3; const float* yp = Ypw + j * 64 + q * 16;
;                         const f32x4 a0 = *(const f32x4*)yp, a1 = *(const f32x4*)(yp + 4), a2 = *(const f32x4*)(yp + 8), a3 = *(const f32x4*)(yp + 12);
;                         const f32x4 ssum = (a0 + a1) + (a2 + a3); const float yv = (ssum.x + ssum.y) + (ssum.z + ssum.w);
;                         const size_t row = (size_t)b * TB + tokof(s, chunk * 64 + pg + j);
;                         Yb[row * D + h * 64 + 32 * half + 4 * wave + q] = (bf16)f2bf(yv);
;                     }
	v_pk_add_f32 v[48:49], v[48:49], v[50:51]
	v_pk_add_f32 v[52:53], v[52:53], v[54:55]
	v_pk_add_f32 v[40:41], v[40:41], v[44:45]
	v_pk_add_f32 v[24:25], v[24:25], v[32:33]
	v_pk_add_f32 v[48:49], v[48:49], v[52:53]
	s_add_i32 s15, s15, s19
	v_pk_add_f32 v[40:41], v[40:41], v[48:49]
	s_nop 0
	v_pk_add_f32 v[24:25], v[24:25], v[40:41] op_sel:[0,1] op_sel_hi:[1,0]
	s_nop 0
	v_cvt_pk_bf16_f32 v244, v24, v25
	s_nop 0
	global_store_dword v243, v244, s[20:21]
	ds_read_b128 v[84:87], v240 offset:13600
	ds_read_b64 v[100:101], v242 offset:48416
	ds_read_b128 v[92:95], v240 offset:31008
	ds_read_b128 v[80:83], v240 offset:4896
	ds_read_b128 v[88:91], v240 offset:22304
	v_pk_mul_f32 v[226:227], v[206:207], v[106:107] op_sel_hi:[1,0]
	v_pk_mul_f32 v[232:233], v[118:119], v[114:115] op_sel_hi:[1,0]
	v_pk_fma_f32 v[226:227], v[208:209], v[106:107], v[226:227] op_sel:[0,1,0]
	v_pk_mul_f32 v[234:235], v[118:119], v[114:115] op_sel:[0,1]
	v_pk_fma_f32 v[226:227], v[210:211], v[108:109], v[226:227] op_sel_hi:[1,0,1]
	v_pk_mul_f32 v[236:237], v[118:119], v[116:117] op_sel_hi:[1,0]
	v_pk_fma_f32 v[226:227], v[212:213], v[108:109], v[226:227] op_sel:[0,1,0]
	v_pk_mul_f32 v[238:239], v[118:119], v[116:117] op_sel:[0,1]
	s_nop 0
	v_add_f32_dpp v230, v227, v226 row_ror:8 row_mask:0xf bank_mask:0xf
	v_pk_fma_f32 v[232:233], v[206:207], v[102:103], v[232:233] op_sel_hi:[1,0,1]
	v_pk_fma_f32 v[234:235], v[208:209], v[102:103], v[234:235] op_sel:[0,1,0]
	v_add_f32_dpp v230, v230, v230 quad_perm:[1,0,3,2] row_mask:0xf bank_mask:0xf
	v_pk_fma_f32 v[236:237], v[210:211], v[104:105], v[236:237] op_sel_hi:[1,0,1]
	v_pk_fma_f32 v[238:239], v[212:213], v[104:105], v[238:239] op_sel:[0,1,0]
	v_add_f32_dpp v230, v230, v230 quad_perm:[2,3,0,1] row_mask:0xf bank_mask:0xf
	ds_read_b128 v[222:225], v240 offset:39440
	s_nop 0
	v_add_f32_dpp v230, v230, v230 row_half_mirror row_mask:0xf bank_mask:0xf
	s_nop 1
	v_mov_b32_dpp v231, v230 row_ror:8 row_mask:0xf bank_mask:0xf
	s_nop 0
	v_pk_fma_f32 v[206:207], v[110:111], v[230:231], v[232:233] op_sel_hi:[0,1,1] neg_lo:[1,0,0] neg_hi:[1,0,0]
	v_pk_fma_f32 v[208:209], v[110:111], v[230:231], v[234:235] op_sel:[1,0,0] neg_lo:[1,0,0] neg_hi:[1,0,0]
	v_pk_fma_f32 v[210:211], v[112:113], v[230:231], v[236:237] op_sel_hi:[0,1,1] neg_lo:[1,0,0] neg_hi:[1,0,0]
	v_pk_fma_f32 v[212:213], v[112:113], v[230:231], v[238:239] op_sel:[1,0,0] neg_lo:[1,0,0] neg_hi:[1,0,0]
	ds_read_b128 v[106:109], v240 offset:13872
	ds_read_b64 v[118:119], v242 offset:48688
	ds_read_b128 v[114:117], v240 offset:31280
	ds_read_b128 v[102:105], v240 offset:5168
	ds_read_b128 v[110:113], v240 offset:22576
	v_pk_mul_f32 v[226:227], v[206:207], v[4:5] op_sel_hi:[1,0]
	v_pk_mul_f32 v[228:229], v[206:207], v[96:97] op_sel_hi:[1,0]
	v_pk_fma_f32 v[226:227], v[208:209], v[4:5], v[226:227] op_sel:[0,1,0]
	v_pk_fma_f32 v[228:229], v[208:209], v[96:97], v[228:229] op_sel:[0,1,0]
	v_pk_fma_f32 v[226:227], v[210:211], v[6:7], v[226:227] op_sel_hi:[1,0,1]
	v_pk_fma_f32 v[228:229], v[210:211], v[98:99], v[228:229] op_sel_hi:[1,0,1]
	v_pk_fma_f32 v[226:227], v[212:213], v[6:7], v[226:227] op_sel:[0,1,0]
	v_pk_fma_f32 v[228:229], v[212:213], v[98:99], v[228:229] op_sel:[0,1,0]
	v_pk_mul_f32 v[232:233], v[16:17], v[12:13] op_sel_hi:[1,0]
	v_add_f32_dpp v230, v227, v226 row_ror:8 row_mask:0xf bank_mask:0xf
	v_pk_mul_f32 v[234:235], v[16:17], v[12:13] op_sel:[0,1]
	v_pk_mul_f32 v[236:237], v[16:17], v[14:15] op_sel_hi:[1,0]
	v_add_f32_dpp v230, v230, v230 quad_perm:[1,0,3,2] row_mask:0xf bank_mask:0xf
	v_pk_mul_f32 v[238:239], v[16:17], v[14:15] op_sel:[0,1]
	ds_read_b128 v[96:99], v240 offset:39712
	v_add_f32_dpp v230, v230, v230 quad_perm:[2,3,0,1] row_mask:0xf bank_mask:0xf
	v_pk_fma_f32 v[232:233], v[206:207], v[0:1], v[232:233] op_sel_hi:[1,0,1]
	v_pk_fma_f32 v[234:235], v[208:209], v[0:1], v[234:235] op_sel:[0,1,0]
	v_add_f32_dpp v230, v230, v230 row_half_mirror row_mask:0xf bank_mask:0xf
	v_pk_fma_f32 v[236:237], v[210:211], v[2:3], v[236:237] op_sel_hi:[1,0,1]
	v_pk_fma_f32 v[238:239], v[212:213], v[2:3], v[238:239] op_sel:[0,1,0]
	v_mov_b32_dpp v231, v230 row_ror:8 row_mask:0xf bank_mask:0xf
	ds_write_b64 v217, v[228:229] offset:0
	v_pk_fma_f32 v[206:207], v[8:9], v[230:231], v[232:233] op_sel_hi:[0,1,1] neg_lo:[1,0,0] neg_hi:[1,0,0]
	v_pk_fma_f32 v[208:209], v[8:9], v[230:231], v[234:235] op_sel:[1,0,0] neg_lo:[1,0,0] neg_hi:[1,0,0]
	v_pk_fma_f32 v[210:211], v[10:11], v[230:231], v[236:237] op_sel_hi:[0,1,1] neg_lo:[1,0,0] neg_hi:[1,0,0]
	v_pk_fma_f32 v[212:213], v[10:11], v[230:231], v[238:239] op_sel:[1,0,0] neg_lo:[1,0,0] neg_hi:[1,0,0]
	s_waitcnt lgkmcnt(7)
; template <int CTRL> __device__ __forceinline__ float dppf(float x) { return __builtin_bit_cast(float, __builtin_amdgcn_update_dpp(0, __builtin_bit_cast(int, x), CTRL, 0xF, 0xF, false)); }
; __device__ __forceinline__ void phase_rwkv_scan(const Fr& F, int jr) {
;     ...
;                 for (int pg = 0; pg < 64; pg += 16) {
; #pragma unroll
;                     for (int pi = 0; pi < 16; ++pi) {
;                         const int p = pg + pi, pn = p < 63 ? p + 1 : 63;
;                         const f32x4 w4n = PW[pn * 16], k4n = PW[1024 + pn * 16], b4n = PW[2048 + pn * 16], d4n = PW[3072 + pn * 16], r4n = PR[pn * 16];
;                         const float vvn = PV[pn * 32];
;                         f32x2 t = S01 * k4.xy; t = S23 * k4.zw + t; float sa = t.x + t.y;
;                         sa += dppf<0x128>(sa);
;                         const f32x2 dv01 = d4.xy * vv, dv23 = d4.zw * vv;
;                         sa += dppf<0x124>(sa);
;                         const f32x2 e01 = S01 * w4.xy + dv01;
;                         sa += dppf<0x122>(sa);
;                         const f32x2 e23 = S23 * w4.zw + dv23;
;                         sa += dppf<0x121>(sa);
;                         S01 = e01 - b4.xy * sa; S23 = e23 - b4.zw * sa;
;                         f32x2 u = S01 * r4.xy; u = S23 * r4.zw + u;
;                         PY[pi * 64] = u.x + u.y;
;                         w4 = w4n; k4 = k4n; b4 = b4n; d4 = d4n; r4 = r4n; vv = vvn;
;                     }
	ds_read_b128 v[4:7], v240 offset:14144
	ds_read_b64 v[16:17], v242 offset:48960
	ds_read_b128 v[12:15], v240 offset:31552
	ds_read_b128 v[0:3], v240 offset:5440
	ds_read_b128 v[8:11], v240 offset:22848
	v_pk_mul_f32 v[226:227], v[206:207], v[84:85] op_sel_hi:[1,0]
	v_pk_mul_f32 v[228:229], v[206:207], v[222:223] op_sel_hi:[1,0]
	v_pk_fma_f32 v[226:227], v[208:209], v[84:85], v[226:227] op_sel:[0,1,0]
	v_pk_fma_f32 v[228:229], v[208:209], v[222:223], v[228:229] op_sel:[0,1,0]
	v_pk_fma_f32 v[226:227], v[210:211], v[86:87], v[226:227] op_sel_hi:[1,0,1]
	v_pk_fma_f32 v[228:229], v[210:211], v[224:225], v[228:229] op_sel_hi:[1,0,1]
	v_pk_fma_f32 v[226:227], v[212:213], v[86:87], v[226:227] op_sel:[0,1,0]
	v_pk_fma_f32 v[228:229], v[212:213], v[224:225], v[228:229] op_sel:[0,1,0]
	v_pk_mul_f32 v[232:233], v[100:101], v[92:93] op_sel_hi:[1,0]
	v_add_f32_dpp v230, v227, v226 row_ror:8 row_mask:0xf bank_mask:0xf
	v_pk_mul_f32 v[234:235], v[100:101], v[92:93] op_sel:[0,1]
	v_pk_mul_f32 v[236:237], v[100:101], v[94:95] op_sel_hi:[1,0]
	v_add_f32_dpp v230, v230, v230 quad_perm:[1,0,3,2] row_mask:0xf bank_mask:0xf
	v_pk_mul_f32 v[238:239], v[100:101], v[94:95] op_sel:[0,1]
	ds_read_b128 v[222:225], v240 offset:39984
	v_add_f32_dpp v230, v230, v230 quad_perm:[2,3,0,1] row_mask:0xf bank_mask:0xf
	v_pk_fma_f32 v[232:233], v[206:207], v[80:81], v[232:233] op_sel_hi:[1,0,1]
	v_pk_fma_f32 v[234:235], v[208:209], v[80:81], v[234:235] op_sel:[0,1,0]
	v_add_f32_dpp v230, v230, v230 row_half_mirror row_mask:0xf bank_mask:0xf
	v_pk_fma_f32 v[236:237], v[210:211], v[82:83], v[236:237] op_sel_hi:[1,0,1]
	v_pk_fma_f32 v[238:239], v[212:213], v[82:83], v[238:239] op_sel:[0,1,0]
	v_mov_b32_dpp v231, v230 row_ror:8 row_mask:0xf bank_mask:0xf
	ds_write_b64 v217, v[228:229] offset:576
	v_pk_fma_f32 v[206:207], v[88:89], v[230:231], v[232:233] op_sel_hi:[0,1,1] neg_lo:[1,0,0] neg_hi:[1,0,0]
	v_pk_fma_f32 v[208:209], v[88:89], v[230:231], v[234:235] op_sel:[1,0,0] neg_lo:[1,0,0] neg_hi:[1,0,0]
	v_pk_fma_f32 v[210:211], v[90:91], v[230:231], v[236:237] op_sel_hi:[0,1,1] neg_lo:[1,0,0] neg_hi:[1,0,0]
	v_pk_fma_f32 v[212:213], v[90:91], v[230:231], v[238:239] op_sel:[1,0,0] neg_lo:[1,0,0] neg_hi:[1,0,0]
	s_waitcnt lgkmcnt(8)
	ds_read_b128 v[84:87], v240 offset:14416
	ds_read_b64 v[100:101], v242 offset:49232
	ds_read_b128 v[92:95], v240 offset:31824
	ds_read_b128 v[80:83], v240 offset:5712
	ds_read_b128 v[88:91], v240 offset:23120
	v_pk_mul_f32 v[226:227], v[206:207], v[106:107] op_sel_hi:[1,0]
	v_pk_mul_f32 v[228:229], v[206:207], v[96:97] op_sel_hi:[1,0]
	v_pk_fma_f32 v[226:227], v[208:209], v[106:107], v[226:227] op_sel:[0,1,0]
	v_pk_fma_f32 v[228:229], v[208:209], v[96:97], v[228:229] op_sel:[0,1,0]
	v_pk_fma_f32 v[226:227], v[210:211], v[108:109], v[226:227] op_sel_hi:[1,0,1]
	v_pk_fma_f32 v[228:229], v[210:211], v[98:99], v[228:229] op_sel_hi:[1,0,1]
	v_pk_fma_f32 v[226:227], v[212:213], v[108:109], v[226:227] op_sel:[0,1,0]
	v_pk_fma_f32 v[228:229], v[212:213], v[98:99], v[228:229] op_sel:[0,1,0]
	v_pk_mul_f32 v[232:233], v[118:119], v[114:115] op_sel_hi:[1,0]
	v_add_f32_dpp v230, v227, v226 row_ror:8 row_mask:0xf bank_mask:0xf
	v_pk_mul_f32 v[234:235], v[118:119], v[114:115] op_sel:[0,1]
	v_pk_mul_f32 v[236:237], v[118:119], v[116:117] op_sel_hi:[1,0]
	v_add_f32_dpp v230, v230, v230 quad_perm:[1,0,3,2] row_mask:0xf bank_mask:0xf
	v_pk_mul_f32 v[238:239], v[118:119], v[116:117] op_sel:[0,1]
	ds_read_b128 v[96:99], v240 offset:40256
	v_add_f32_dpp v230, v230, v230 quad_perm:[2,3,0,1] row_mask:0xf bank_mask:0xf
	v_pk_fma_f32 v[232:233], v[206:207], v[102:103], v[232:233] op_sel_hi:[1,0,1]
	v_pk_fma_f32 v[234:235], v[208:209], v[102:103], v[234:235] op_sel:[0,1,0]
	v_add_f32_dpp v230, v230, v230 row_half_mirror row_mask:0xf bank_mask:0xf
	v_pk_fma_f32 v[236:237], v[210:211], v[104:105], v[236:237] op_sel_hi:[1,0,1]
	v_pk_fma_f32 v[238:239], v[212:213], v[104:105], v[238:239] op_sel:[0,1,0]
	v_mov_b32_dpp v231, v230 row_ror:8 row_mask:0xf bank_mask:0xf
	ds_write_b64 v217, v[228:229] offset:1152
	v_pk_fma_f32 v[206:207], v[110:111], v[230:231], v[232:233] op_sel_hi:[0,1,1] neg_lo:[1,0,0] neg_hi:[1,0,0]
	v_pk_fma_f32 v[208:209], v[110:111], v[230:231], v[234:235] op_sel:[1,0,0] neg_lo:[1,0,0] neg_hi:[1,0,0]
	v_pk_fma_f32 v[210:211], v[112:113], v[230:231], v[236:237] op_sel_hi:[0,1,1] neg_lo:[1,0,0] neg_hi:[1,0,0]
	v_pk_fma_f32 v[212:213], v[112:113], v[230:231], v[238:239] op_sel:[1,0,0] neg_lo:[1,0,0] neg_hi:[1,0,0]
	s_waitcnt lgkmcnt(8)
	ds_read_b128 v[106:109], v240 offset:14688
	ds_read_b64 v[118:119], v242 offset:49504
	ds_read_b128 v[114:117], v240 offset:32096
	ds_read_b128 v[102:105], v240 offset:5984
	ds_read_b128 v[110:113], v240 offset:23392
	v_pk_mul_f32 v[226:227], v[206:207], v[4:5] op_sel_hi:[1,0]
	v_pk_mul_f32 v[228:229], v[206:207], v[222:223] op_sel_hi:[1,0]
	v_pk_fma_f32 v[226:227], v[208:209], v[4:5], v[226:227] op_sel:[0,1,0]
	v_pk_fma_f32 v[228:229], v[208:209], v[222:223], v[228:229] op_sel:[0,1,0]
	v_pk_fma_f32 v[226:227], v[210:211], v[6:7], v[226:227] op_sel_hi:[1,0,1]
	v_pk_fma_f32 v[228:229], v[210:211], v[224:225], v[228:229] op_sel_hi:[1,0,1]
	v_pk_fma_f32 v[226:227], v[212:213], v[6:7], v[226:227] op_sel:[0,1,0]
	v_pk_fma_f32 v[228:229], v[212:213], v[224:225], v[228:229] op_sel:[0,1,0]
	v_pk_mul_f32 v[232:233], v[16:17], v[12:13] op_sel_hi:[1,0]
	v_add_f32_dpp v230, v227, v226 row_ror:8 row_mask:0xf bank_mask:0xf
	v_pk_mul_f32 v[234:235], v[16:17], v[12:13] op_sel:[0,1]
	v_pk_mul_f32 v[236:237], v[16:17], v[14:15] op_sel_hi:[1,0]
	v_add_f32_dpp v230, v230, v230 quad_perm:[1,0,3,2] row_mask:0xf bank_mask:0xf
	v_pk_mul_f32 v[238:239], v[16:17], v[14:15] op_sel:[0,1]
	ds_read_b128 v[222:225], v240 offset:40528
	v_add_f32_dpp v230, v230, v230 quad_perm:[2,3,0,1] row_mask:0xf bank_mask:0xf
	v_pk_fma_f32 v[232:233], v[206:207], v[0:1], v[232:233] op_sel_hi:[1,0,1]
	v_pk_fma_f32 v[234:235], v[208:209], v[0:1], v[234:235] op_sel:[0,1,0]
	v_add_f32_dpp v230, v230, v230 row_half_mirror row_mask:0xf bank_mask:0xf
	v_pk_fma_f32 v[236:237], v[210:211], v[2:3], v[236:237] op_sel_hi:[1,0,1]
	v_pk_fma_f32 v[238:239], v[212:213], v[2:3], v[238:239] op_sel:[0,1,0]
	v_mov_b32_dpp v231, v230 row_ror:8 row_mask:0xf bank_mask:0xf
	ds_write_b64 v217, v[228:229] offset:1728
	v_pk_fma_f32 v[206:207], v[8:9], v[230:231], v[232:233] op_sel_hi:[0,1,1] neg_lo:[1,0,0] neg_hi:[1,0,0]
	v_pk_fma_f32 v[208:209], v[8:9], v[230:231], v[234:235] op_sel:[1,0,0] neg_lo:[1,0,0] neg_hi:[1,0,0]
	v_pk_fma_f32 v[210:211], v[10:11], v[230:231], v[236:237] op_sel_hi:[0,1,1] neg_lo:[1,0,0] neg_hi:[1,0,0]
	v_pk_fma_f32 v[212:213], v[10:11], v[230:231], v[238:239] op_sel:[1,0,0] neg_lo:[1,0,0] neg_hi:[1,0,0]
	s_waitcnt lgkmcnt(8)
; template <int CTRL> __device__ __forceinline__ float dppf(float x) { return __builtin_bit_cast(float, __builtin_amdgcn_update_dpp(0, __builtin_bit_cast(int, x), CTRL, 0xF, 0xF, false)); }
; __device__ __forceinline__ void phase_rwkv_scan(const Fr& F, int jr) {
;     ...
;                 for (int pg = 0; pg < 64; pg += 16) {
; #pragma unroll
;                     for (int pi = 0; pi < 16; ++pi) {
;                         const int p = pg + pi, pn = p < 63 ? p + 1 : 63;
;                         const f32x4 w4n = PW[pn * 16], k4n = PW[1024 + pn * 16], b4n = PW[2048 + pn * 16], d4n = PW[3072 + pn * 16], r4n = PR[pn * 16];
;                         const float vvn = PV[pn * 32];
;                         f32x2 t = S01 * k4.xy; t = S23 * k4.zw + t; float sa = t.x + t.y;
;                         sa += dppf<0x128>(sa);
;                         const f32x2 dv01 = d4.xy * vv, dv23 = d4.zw * vv;
;                         sa += dppf<0x124>(sa);
;                         const f32x2 e01 = S01 * w4.xy + dv01;
;                         sa += dppf<0x122>(sa);
;                         const f32x2 e23 = S23 * w4.zw + dv23;
;                         sa += dppf<0x121>(sa);
;                         S01 = e01 - b4.xy * sa; S23 = e23 - b4.zw * sa;
;                         f32x2 u = S01 * r4.xy; u = S23 * r4.zw + u;
;                         PY[pi * 64] = u.x + u.y;
;                         w4 = w4n; k4 = k4n; b4 = b4n; d4 = d4n; r4 = r4n; vv = vvn;
;                     }
	ds_read_b128 v[4:7], v240 offset:14960
	ds_read_b64 v[16:17], v242 offset:49776
	ds_read_b128 v[12:15], v240 offset:32368
	ds_read_b128 v[0:3], v240 offset:6256
	ds_read_b128 v[8:11], v240 offset:23664
	v_pk_mul_f32 v[226:227], v[206:207], v[84:85] op_sel_hi:[1,0]
	v_pk_mul_f32 v[228:229], v[206:207], v[96:97] op_sel_hi:[1,0]
	v_pk_fma_f32 v[226:227], v[208:209], v[84:85], v[226:227] op_sel:[0,1,0]
	v_pk_fma_f32 v[228:229], v[208:209], v[96:97], v[228:229] op_sel:[0,1,0]
	v_pk_fma_f32 v[226:227], v[210:211], v[86:87], v[226:227] op_sel_hi:[1,0,1]
	v_pk_fma_f32 v[228:229], v[210:211], v[98:99], v[228:229] op_sel_hi:[1,0,1]
	v_pk_fma_f32 v[226:227], v[212:213], v[86:87], v[226:227] op_sel:[0,1,0]
	v_pk_fma_f32 v[228:229], v[212:213], v[98:99], v[228:229] op_sel:[0,1,0]
	v_pk_mul_f32 v[232:233], v[100:101], v[92:93] op_sel_hi:[1,0]
	v_add_f32_dpp v230, v227, v226 row_ror:8 row_mask:0xf bank_mask:0xf
	v_pk_mul_f32 v[234:235], v[100:101], v[92:93] op_sel:[0,1]
	v_pk_mul_f32 v[236:237], v[100:101], v[94:95] op_sel_hi:[1,0]
	v_add_f32_dpp v230, v230, v230 quad_perm:[1,0,3,2] row_mask:0xf bank_mask:0xf
	v_pk_mul_f32 v[238:239], v[100:101], v[94:95] op_sel:[0,1]
	ds_read_b128 v[96:99], v240 offset:40800
	v_add_f32_dpp v230, v230, v230 quad_perm:[2,3,0,1] row_mask:0xf bank_mask:0xf
	v_pk_fma_f32 v[232:233], v[206:207], v[80:81], v[232:233] op_sel_hi:[1,0,1]
	v_pk_fma_f32 v[234:235], v[208:209], v[80:81], v[234:235] op_sel:[0,1,0]
	v_add_f32_dpp v230, v230, v230 row_half_mirror row_mask:0xf bank_mask:0xf
	v_pk_fma_f32 v[236:237], v[210:211], v[82:83], v[236:237] op_sel_hi:[1,0,1]
	v_pk_fma_f32 v[238:239], v[212:213], v[82:83], v[238:239] op_sel:[0,1,0]
	v_mov_b32_dpp v231, v230 row_ror:8 row_mask:0xf bank_mask:0xf
	ds_write_b64 v217, v[228:229] offset:2304
	v_pk_fma_f32 v[206:207], v[88:89], v[230:231], v[232:233] op_sel_hi:[0,1,1] neg_lo:[1,0,0] neg_hi:[1,0,0]
	v_pk_fma_f32 v[208:209], v[88:89], v[230:231], v[234:235] op_sel:[1,0,0] neg_lo:[1,0,0] neg_hi:[1,0,0]
	v_pk_fma_f32 v[210:211], v[90:91], v[230:231], v[236:237] op_sel_hi:[0,1,1] neg_lo:[1,0,0] neg_hi:[1,0,0]
	v_pk_fma_f32 v[212:213], v[90:91], v[230:231], v[238:239] op_sel:[1,0,0] neg_lo:[1,0,0] neg_hi:[1,0,0]
	s_waitcnt lgkmcnt(8)
	ds_read_b128 v[84:87], v240 offset:15232
	ds_read_b64 v[100:101], v242 offset:50048
	ds_read_b128 v[92:95], v240 offset:32640
	ds_read_b128 v[80:83], v240 offset:6528
	ds_read_b128 v[88:91], v240 offset:23936
	v_pk_mul_f32 v[226:227], v[206:207], v[106:107] op_sel_hi:[1,0]
	v_pk_mul_f32 v[228:229], v[206:207], v[222:223] op_sel_hi:[1,0]
	v_pk_fma_f32 v[226:227], v[208:209], v[106:107], v[226:227] op_sel:[0,1,0]
	v_pk_fma_f32 v[228:229], v[208:209], v[222:223], v[228:229] op_sel:[0,1,0]
	v_pk_fma_f32 v[226:227], v[210:211], v[108:109], v[226:227] op_sel_hi:[1,0,1]
	v_pk_fma_f32 v[228:229], v[210:211], v[224:225], v[228:229] op_sel_hi:[1,0,1]
	v_pk_fma_f32 v[226:227], v[212:213], v[108:109], v[226:227] op_sel:[0,1,0]
	v_pk_fma_f32 v[228:229], v[212:213], v[224:225], v[228:229] op_sel:[0,1,0]
	v_pk_mul_f32 v[232:233], v[118:119], v[114:115] op_sel_hi:[1,0]
	v_add_f32_dpp v230, v227, v226 row_ror:8 row_mask:0xf bank_mask:0xf
	v_pk_mul_f32 v[234:235], v[118:119], v[114:115] op_sel:[0,1]
	v_pk_mul_f32 v[236:237], v[118:119], v[116:117] op_sel_hi:[1,0]
	v_add_f32_dpp v230, v230, v230 quad_perm:[1,0,3,2] row_mask:0xf bank_mask:0xf
	v_pk_mul_f32 v[238:239], v[118:119], v[116:117] op_sel:[0,1]
	ds_read_b128 v[222:225], v240 offset:41072
	v_add_f32_dpp v230, v230, v230 quad_perm:[2,3,0,1] row_mask:0xf bank_mask:0xf
	v_pk_fma_f32 v[232:233], v[206:207], v[102:103], v[232:233] op_sel_hi:[1,0,1]
	v_pk_fma_f32 v[234:235], v[208:209], v[102:103], v[234:235] op_sel:[0,1,0]
	v_add_f32_dpp v230, v230, v230 row_half_mirror row_mask:0xf bank_mask:0xf
	v_pk_fma_f32 v[236:237], v[210:211], v[104:105], v[236:237] op_sel_hi:[1,0,1]
	v_pk_fma_f32 v[238:239], v[212:213], v[104:105], v[238:239] op_sel:[0,1,0]
	v_mov_b32_dpp v231, v230 row_ror:8 row_mask:0xf bank_mask:0xf
	ds_write_b64 v217, v[228:229] offset:2880
	v_pk_fma_f32 v[206:207], v[110:111], v[230:231], v[232:233] op_sel_hi:[0,1,1] neg_lo:[1,0,0] neg_hi:[1,0,0]
	v_pk_fma_f32 v[208:209], v[110:111], v[230:231], v[234:235] op_sel:[1,0,0] neg_lo:[1,0,0] neg_hi:[1,0,0]
	v_pk_fma_f32 v[210:211], v[112:113], v[230:231], v[236:237] op_sel_hi:[0,1,1] neg_lo:[1,0,0] neg_hi:[1,0,0]
	v_pk_fma_f32 v[212:213], v[112:113], v[230:231], v[238:239] op_sel:[1,0,0] neg_lo:[1,0,0] neg_hi:[1,0,0]
	s_waitcnt lgkmcnt(8)
	ds_read_b128 v[106:109], v240 offset:15504
	ds_read_b64 v[118:119], v242 offset:50320
	ds_read_b128 v[114:117], v240 offset:32912
	ds_read_b128 v[102:105], v240 offset:6800
	ds_read_b128 v[110:113], v240 offset:24208
	v_pk_mul_f32 v[226:227], v[206:207], v[4:5] op_sel_hi:[1,0]
	v_pk_mul_f32 v[228:229], v[206:207], v[96:97] op_sel_hi:[1,0]
	v_pk_fma_f32 v[226:227], v[208:209], v[4:5], v[226:227] op_sel:[0,1,0]
	v_pk_fma_f32 v[228:229], v[208:209], v[96:97], v[228:229] op_sel:[0,1,0]
	v_pk_fma_f32 v[226:227], v[210:211], v[6:7], v[226:227] op_sel_hi:[1,0,1]
	v_pk_fma_f32 v[228:229], v[210:211], v[98:99], v[228:229] op_sel_hi:[1,0,1]
	v_pk_fma_f32 v[226:227], v[212:213], v[6:7], v[226:227] op_sel:[0,1,0]
	v_pk_fma_f32 v[228:229], v[212:213], v[98:99], v[228:229] op_sel:[0,1,0]
	v_pk_mul_f32 v[232:233], v[16:17], v[12:13] op_sel_hi:[1,0]
	v_add_f32_dpp v230, v227, v226 row_ror:8 row_mask:0xf bank_mask:0xf
	v_pk_mul_f32 v[234:235], v[16:17], v[12:13] op_sel:[0,1]
	v_pk_mul_f32 v[236:237], v[16:17], v[14:15] op_sel_hi:[1,0]
	v_add_f32_dpp v230, v230, v230 quad_perm:[1,0,3,2] row_mask:0xf bank_mask:0xf
	v_pk_mul_f32 v[238:239], v[16:17], v[14:15] op_sel:[0,1]
	ds_read_b128 v[96:99], v240 offset:41344
	v_add_f32_dpp v230, v230, v230 quad_perm:[2,3,0,1] row_mask:0xf bank_mask:0xf
	v_pk_fma_f32 v[232:233], v[206:207], v[0:1], v[232:233] op_sel_hi:[1,0,1]
	v_pk_fma_f32 v[234:235], v[208:209], v[0:1], v[234:235] op_sel:[0,1,0]
	v_add_f32_dpp v230, v230, v230 row_half_mirror row_mask:0xf bank_mask:0xf
	v_pk_fma_f32 v[236:237], v[210:211], v[2:3], v[236:237] op_sel_hi:[1,0,1]
	v_pk_fma_f32 v[238:239], v[212:213], v[2:3], v[238:239] op_sel:[0,1,0]
	v_mov_b32_dpp v231, v230 row_ror:8 row_mask:0xf bank_mask:0xf
	ds_write_b64 v217, v[228:229] offset:3456
	v_pk_fma_f32 v[206:207], v[8:9], v[230:231], v[232:233] op_sel_hi:[0,1,1] neg_lo:[1,0,0] neg_hi:[1,0,0]
	v_pk_fma_f32 v[208:209], v[8:9], v[230:231], v[234:235] op_sel:[1,0,0] neg_lo:[1,0,0] neg_hi:[1,0,0]
	v_pk_fma_f32 v[210:211], v[10:11], v[230:231], v[236:237] op_sel_hi:[0,1,1] neg_lo:[1,0,0] neg_hi:[1,0,0]
	v_pk_fma_f32 v[212:213], v[10:11], v[230:231], v[238:239] op_sel:[1,0,0] neg_lo:[1,0,0] neg_hi:[1,0,0]
	s_waitcnt lgkmcnt(8)
; template <int CTRL> __device__ __forceinline__ float dppf(float x) { return __builtin_bit_cast(float, __builtin_amdgcn_update_dpp(0, __builtin_bit_cast(int, x), CTRL, 0xF, 0xF, false)); }
; __device__ __forceinline__ void phase_rwkv_scan(const Fr& F, int jr) {
;     ...
;                 for (int pg = 0; pg < 64; pg += 16) {
; #pragma unroll
;                     for (int pi = 0; pi < 16; ++pi) {
;                         const int p = pg + pi, pn = p < 63 ? p + 1 : 63;
;                         const f32x4 w4n = PW[pn * 16], k4n = PW[1024 + pn * 16], b4n = PW[2048 + pn * 16], d4n = PW[3072 + pn * 16], r4n = PR[pn * 16];
;                         const float vvn = PV[pn * 32];
;                         f32x2 t = S01 * k4.xy; t = S23 * k4.zw + t; float sa = t.x + t.y;
;                         sa += dppf<0x128>(sa);
;                         const f32x2 dv01 = d4.xy * vv, dv23 = d4.zw * vv;
;                         sa += dppf<0x124>(sa);
;                         const f32x2 e01 = S01 * w4.xy + dv01;
;                         sa += dppf<0x122>(sa);
;                         const f32x2 e23 = S23 * w4.zw + dv23;
;                         sa += dppf<0x121>(sa);
;                         S01 = e01 - b4.xy * sa; S23 = e23 - b4.zw * sa;
;                         f32x2 u = S01 * r4.xy; u = S23 * r4.zw + u;
;                         PY[pi * 64] = u.x + u.y;
;                         w4 = w4n; k4 = k4n; b4 = b4n; d4 = d4n; r4 = r4n; vv = vvn;
;                     }
	ds_read_b128 v[4:7], v240 offset:15776
	ds_read_b64 v[16:17], v242 offset:50592
	ds_read_b128 v[12:15], v240 offset:33184
	ds_read_b128 v[0:3], v240 offset:7072
	ds_read_b128 v[8:11], v240 offset:24480
	v_pk_mul_f32 v[226:227], v[206:207], v[84:85] op_sel_hi:[1,0]
	v_pk_mul_f32 v[228:229], v[206:207], v[222:223] op_sel_hi:[1,0]
	v_pk_fma_f32 v[226:227], v[208:209], v[84:85], v[226:227] op_sel:[0,1,0]
	v_pk_fma_f32 v[228:229], v[208:209], v[222:223], v[228:229] op_sel:[0,1,0]
	v_pk_fma_f32 v[226:227], v[210:211], v[86:87], v[226:227] op_sel_hi:[1,0,1]
	v_pk_fma_f32 v[228:229], v[210:211], v[224:225], v[228:229] op_sel_hi:[1,0,1]
	v_pk_fma_f32 v[226:227], v[212:213], v[86:87], v[226:227] op_sel:[0,1,0]
	v_pk_fma_f32 v[228:229], v[212:213], v[224:225], v[228:229] op_sel:[0,1,0]
	v_pk_mul_f32 v[232:233], v[100:101], v[92:93] op_sel_hi:[1,0]
	v_add_f32_dpp v230, v227, v226 row_ror:8 row_mask:0xf bank_mask:0xf
	v_pk_mul_f32 v[234:235], v[100:101], v[92:93] op_sel:[0,1]
	v_pk_mul_f32 v[236:237], v[100:101], v[94:95] op_sel_hi:[1,0]
	v_add_f32_dpp v230, v230, v230 quad_perm:[1,0,3,2] row_mask:0xf bank_mask:0xf
	v_pk_mul_f32 v[238:239], v[100:101], v[94:95] op_sel:[0,1]
	ds_read_b128 v[222:225], v240 offset:41616
	v_add_f32_dpp v230, v230, v230 quad_perm:[2,3,0,1] row_mask:0xf bank_mask:0xf
	v_pk_fma_f32 v[232:233], v[206:207], v[80:81], v[232:233] op_sel_hi:[1,0,1]
	v_pk_fma_f32 v[234:235], v[208:209], v[80:81], v[234:235] op_sel:[0,1,0]
	v_add_f32_dpp v230, v230, v230 row_half_mirror row_mask:0xf bank_mask:0xf
	v_pk_fma_f32 v[236:237], v[210:211], v[82:83], v[236:237] op_sel_hi:[1,0,1]
	v_pk_fma_f32 v[238:239], v[212:213], v[82:83], v[238:239] op_sel:[0,1,0]
	v_mov_b32_dpp v231, v230 row_ror:8 row_mask:0xf bank_mask:0xf
	ds_write_b64 v217, v[228:229] offset:4032
	v_pk_fma_f32 v[206:207], v[88:89], v[230:231], v[232:233] op_sel_hi:[0,1,1] neg_lo:[1,0,0] neg_hi:[1,0,0]
	v_pk_fma_f32 v[208:209], v[88:89], v[230:231], v[234:235] op_sel:[1,0,0] neg_lo:[1,0,0] neg_hi:[1,0,0]
	v_pk_fma_f32 v[210:211], v[90:91], v[230:231], v[236:237] op_sel_hi:[0,1,1] neg_lo:[1,0,0] neg_hi:[1,0,0]
	v_pk_fma_f32 v[212:213], v[90:91], v[230:231], v[238:239] op_sel:[1,0,0] neg_lo:[1,0,0] neg_hi:[1,0,0]
	s_waitcnt lgkmcnt(8)
	ds_read_b128 v[84:87], v240 offset:16048
	ds_read_b64 v[100:101], v242 offset:50864
	ds_read_b128 v[92:95], v240 offset:33456
	ds_read_b128 v[80:83], v240 offset:7344
	ds_read_b128 v[88:91], v240 offset:24752
	v_pk_mul_f32 v[226:227], v[206:207], v[106:107] op_sel_hi:[1,0]
	v_pk_mul_f32 v[228:229], v[206:207], v[96:97] op_sel_hi:[1,0]
	v_pk_fma_f32 v[226:227], v[208:209], v[106:107], v[226:227] op_sel:[0,1,0]
	v_pk_fma_f32 v[228:229], v[208:209], v[96:97], v[228:229] op_sel:[0,1,0]
	v_pk_fma_f32 v[226:227], v[210:211], v[108:109], v[226:227] op_sel_hi:[1,0,1]
	v_pk_fma_f32 v[228:229], v[210:211], v[98:99], v[228:229] op_sel_hi:[1,0,1]
	v_pk_fma_f32 v[226:227], v[212:213], v[108:109], v[226:227] op_sel:[0,1,0]
	v_pk_fma_f32 v[228:229], v[212:213], v[98:99], v[228:229] op_sel:[0,1,0]
	v_pk_mul_f32 v[232:233], v[118:119], v[114:115] op_sel_hi:[1,0]
	v_add_f32_dpp v230, v227, v226 row_ror:8 row_mask:0xf bank_mask:0xf
	v_pk_mul_f32 v[234:235], v[118:119], v[114:115] op_sel:[0,1]
	v_pk_mul_f32 v[236:237], v[118:119], v[116:117] op_sel_hi:[1,0]
	v_add_f32_dpp v230, v230, v230 quad_perm:[1,0,3,2] row_mask:0xf bank_mask:0xf
	v_pk_mul_f32 v[238:239], v[118:119], v[116:117] op_sel:[0,1]
	ds_read_b128 v[96:99], v240 offset:41888
	v_add_f32_dpp v230, v230, v230 quad_perm:[2,3,0,1] row_mask:0xf bank_mask:0xf
	v_pk_fma_f32 v[232:233], v[206:207], v[102:103], v[232:233] op_sel_hi:[1,0,1]
	v_pk_fma_f32 v[234:235], v[208:209], v[102:103], v[234:235] op_sel:[0,1,0]
	v_add_f32_dpp v230, v230, v230 row_half_mirror row_mask:0xf bank_mask:0xf
	v_pk_fma_f32 v[236:237], v[210:211], v[104:105], v[236:237] op_sel_hi:[1,0,1]
	v_pk_fma_f32 v[238:239], v[212:213], v[104:105], v[238:239] op_sel:[0,1,0]
	v_mov_b32_dpp v231, v230 row_ror:8 row_mask:0xf bank_mask:0xf
	ds_write_b64 v217, v[228:229] offset:4608
	v_pk_fma_f32 v[206:207], v[110:111], v[230:231], v[232:233] op_sel_hi:[0,1,1] neg_lo:[1,0,0] neg_hi:[1,0,0]
	v_pk_fma_f32 v[208:209], v[110:111], v[230:231], v[234:235] op_sel:[1,0,0] neg_lo:[1,0,0] neg_hi:[1,0,0]
	v_pk_fma_f32 v[210:211], v[112:113], v[230:231], v[236:237] op_sel_hi:[0,1,1] neg_lo:[1,0,0] neg_hi:[1,0,0]
	v_pk_fma_f32 v[212:213], v[112:113], v[230:231], v[238:239] op_sel:[1,0,0] neg_lo:[1,0,0] neg_hi:[1,0,0]
	s_waitcnt lgkmcnt(8)
	ds_read_b128 v[106:109], v240 offset:16320
	ds_read_b64 v[118:119], v242 offset:51136
	ds_read_b128 v[114:117], v240 offset:33728
	ds_read_b128 v[102:105], v240 offset:7616
	ds_read_b128 v[110:113], v240 offset:25024
	v_pk_mul_f32 v[226:227], v[206:207], v[4:5] op_sel_hi:[1,0]
	v_pk_mul_f32 v[228:229], v[206:207], v[222:223] op_sel_hi:[1,0]
	v_pk_fma_f32 v[226:227], v[208:209], v[4:5], v[226:227] op_sel:[0,1,0]
	v_pk_fma_f32 v[228:229], v[208:209], v[222:223], v[228:229] op_sel:[0,1,0]
	v_pk_fma_f32 v[226:227], v[210:211], v[6:7], v[226:227] op_sel_hi:[1,0,1]
	v_pk_fma_f32 v[228:229], v[210:211], v[224:225], v[228:229] op_sel_hi:[1,0,1]
	v_pk_fma_f32 v[226:227], v[212:213], v[6:7], v[226:227] op_sel:[0,1,0]
	v_pk_fma_f32 v[228:229], v[212:213], v[224:225], v[228:229] op_sel:[0,1,0]
	v_pk_mul_f32 v[232:233], v[16:17], v[12:13] op_sel_hi:[1,0]
	v_add_f32_dpp v230, v227, v226 row_ror:8 row_mask:0xf bank_mask:0xf
	v_pk_mul_f32 v[234:235], v[16:17], v[12:13] op_sel:[0,1]
	v_pk_mul_f32 v[236:237], v[16:17], v[14:15] op_sel_hi:[1,0]
	v_add_f32_dpp v230, v230, v230 quad_perm:[1,0,3,2] row_mask:0xf bank_mask:0xf
	v_pk_mul_f32 v[238:239], v[16:17], v[14:15] op_sel:[0,1]
	ds_read_b128 v[222:225], v240 offset:42160
	v_add_f32_dpp v230, v230, v230 quad_perm:[2,3,0,1] row_mask:0xf bank_mask:0xf
	v_pk_fma_f32 v[232:233], v[206:207], v[0:1], v[232:233] op_sel_hi:[1,0,1]
	v_pk_fma_f32 v[234:235], v[208:209], v[0:1], v[234:235] op_sel:[0,1,0]
	v_add_f32_dpp v230, v230, v230 row_half_mirror row_mask:0xf bank_mask:0xf
	v_pk_fma_f32 v[236:237], v[210:211], v[2:3], v[236:237] op_sel_hi:[1,0,1]
	v_pk_fma_f32 v[238:239], v[212:213], v[2:3], v[238:239] op_sel:[0,1,0]
	v_mov_b32_dpp v231, v230 row_ror:8 row_mask:0xf bank_mask:0xf
	ds_write_b64 v217, v[228:229] offset:5184
	v_pk_fma_f32 v[206:207], v[8:9], v[230:231], v[232:233] op_sel_hi:[0,1,1] neg_lo:[1,0,0] neg_hi:[1,0,0]
	v_pk_fma_f32 v[208:209], v[8:9], v[230:231], v[234:235] op_sel:[1,0,0] neg_lo:[1,0,0] neg_hi:[1,0,0]
	v_pk_fma_f32 v[210:211], v[10:11], v[230:231], v[236:237] op_sel_hi:[0,1,1] neg_lo:[1,0,0] neg_hi:[1,0,0]
	v_pk_fma_f32 v[212:213], v[10:11], v[230:231], v[238:239] op_sel:[1,0,0] neg_lo:[1,0,0] neg_hi:[1,0,0]
	s_waitcnt lgkmcnt(8)
; template <int CTRL> __device__ __forceinline__ float dppf(float x) { return __builtin_bit_cast(float, __builtin_amdgcn_update_dpp(0, __builtin_bit_cast(int, x), CTRL, 0xF, 0xF, false)); }
; __device__ __forceinline__ void phase_rwkv_scan(const Fr& F, int jr) {
;     ...
;                         const int p = pg + pi, pn = p < 63 ? p + 1 : 63;
;                         const f32x4 w4n = PW[pn * 16], k4n = PW[1024 + pn * 16], b4n = PW[2048 + pn * 16], d4n = PW[3072 + pn * 16], r4n = PR[pn * 16];
;                         const float vvn = PV[pn * 32];
;                         f32x2 t = S01 * k4.xy; t = S23 * k4.zw + t; float sa = t.x + t.y;
;                         sa += dppf<0x128>(sa);
;                         const f32x2 dv01 = d4.xy * vv, dv23 = d4.zw * vv;
;                         sa += dppf<0x124>(sa);
;                         const f32x2 e01 = S01 * w4.xy + dv01;
;                         sa += dppf<0x122>(sa);
;                         const f32x2 e23 = S23 * w4.zw + dv23;
;                         sa += dppf<0x121>(sa);
;                         S01 = e01 - b4.xy * sa; S23 = e23 - b4.zw * sa;
;                         f32x2 u = S01 * r4.xy; u = S23 * r4.zw + u;
;                         PY[pi * 64] = u.x + u.y;
;                         w4 = w4n; k4 = k4n; b4 = b4n; d4 = d4n; r4 = r4n; vv = vvn;
	ds_read_b128 v[4:7], v240 offset:16592
	ds_read_b64 v[16:17], v242 offset:51408
	ds_read_b128 v[12:15], v240 offset:34000
	ds_read_b128 v[0:3], v240 offset:7888
	ds_read_b128 v[8:11], v240 offset:25296
	v_pk_mul_f32 v[226:227], v[206:207], v[84:85] op_sel_hi:[1,0]
	v_pk_mul_f32 v[228:229], v[206:207], v[96:97] op_sel_hi:[1,0]
	v_pk_fma_f32 v[226:227], v[208:209], v[84:85], v[226:227] op_sel:[0,1,0]
	v_pk_fma_f32 v[228:229], v[208:209], v[96:97], v[228:229] op_sel:[0,1,0]
	v_pk_fma_f32 v[226:227], v[210:211], v[86:87], v[226:227] op_sel_hi:[1,0,1]
	v_pk_fma_f32 v[228:229], v[210:211], v[98:99], v[228:229] op_sel_hi:[1,0,1]
	v_pk_fma_f32 v[226:227], v[212:213], v[86:87], v[226:227] op_sel:[0,1,0]
	v_pk_fma_f32 v[228:229], v[212:213], v[98:99], v[228:229] op_sel:[0,1,0]
	v_pk_mul_f32 v[232:233], v[100:101], v[92:93] op_sel_hi:[1,0]
	v_add_f32_dpp v230, v227, v226 row_ror:8 row_mask:0xf bank_mask:0xf
	v_pk_mul_f32 v[234:235], v[100:101], v[92:93] op_sel:[0,1]
	v_pk_mul_f32 v[236:237], v[100:101], v[94:95] op_sel_hi:[1,0]
	v_add_f32_dpp v230, v230, v230 quad_perm:[1,0,3,2] row_mask:0xf bank_mask:0xf
	v_pk_mul_f32 v[238:239], v[100:101], v[94:95] op_sel:[0,1]
	ds_read_b128 v[96:99], v240 offset:42432
	v_add_f32_dpp v230, v230, v230 quad_perm:[2,3,0,1] row_mask:0xf bank_mask:0xf
	v_pk_fma_f32 v[232:233], v[206:207], v[80:81], v[232:233] op_sel_hi:[1,0,1]
	v_pk_fma_f32 v[234:235], v[208:209], v[80:81], v[234:235] op_sel:[0,1,0]
	v_add_f32_dpp v230, v230, v230 row_half_mirror row_mask:0xf bank_mask:0xf
	v_pk_fma_f32 v[236:237], v[210:211], v[82:83], v[236:237] op_sel_hi:[1,0,1]
	v_pk_fma_f32 v[238:239], v[212:213], v[82:83], v[238:239] op_sel:[0,1,0]
	v_mov_b32_dpp v231, v230 row_ror:8 row_mask:0xf bank_mask:0xf
	ds_write_b64 v217, v[228:229] offset:5760
	v_pk_fma_f32 v[206:207], v[88:89], v[230:231], v[232:233] op_sel_hi:[0,1,1] neg_lo:[1,0,0] neg_hi:[1,0,0]
	v_pk_fma_f32 v[208:209], v[88:89], v[230:231], v[234:235] op_sel:[1,0,0] neg_lo:[1,0,0] neg_hi:[1,0,0]
	v_pk_fma_f32 v[210:211], v[90:91], v[230:231], v[236:237] op_sel_hi:[0,1,1] neg_lo:[1,0,0] neg_hi:[1,0,0]
	v_pk_fma_f32 v[212:213], v[90:91], v[230:231], v[238:239] op_sel:[1,0,0] neg_lo:[1,0,0] neg_hi:[1,0,0]
	s_waitcnt lgkmcnt(8)
	ds_read_b128 v[84:87], v240 offset:16864
	ds_read_b64 v[100:101], v242 offset:51680
	ds_read_b128 v[92:95], v240 offset:34272
	ds_read_b128 v[80:83], v240 offset:8160
	ds_read_b128 v[88:91], v240 offset:25568
	v_pk_mul_f32 v[226:227], v[206:207], v[106:107] op_sel_hi:[1,0]
	v_pk_mul_f32 v[228:229], v[206:207], v[222:223] op_sel_hi:[1,0]
	v_pk_fma_f32 v[226:227], v[208:209], v[106:107], v[226:227] op_sel:[0,1,0]
	v_pk_fma_f32 v[228:229], v[208:209], v[222:223], v[228:229] op_sel:[0,1,0]
	v_pk_fma_f32 v[226:227], v[210:211], v[108:109], v[226:227] op_sel_hi:[1,0,1]
	v_pk_fma_f32 v[228:229], v[210:211], v[224:225], v[228:229] op_sel_hi:[1,0,1]
	v_pk_fma_f32 v[226:227], v[212:213], v[108:109], v[226:227] op_sel:[0,1,0]
	v_pk_fma_f32 v[228:229], v[212:213], v[224:225], v[228:229] op_sel:[0,1,0]
	v_pk_mul_f32 v[232:233], v[118:119], v[114:115] op_sel_hi:[1,0]
	v_add_f32_dpp v230, v227, v226 row_ror:8 row_mask:0xf bank_mask:0xf
	v_pk_mul_f32 v[234:235], v[118:119], v[114:115] op_sel:[0,1]
	v_pk_mul_f32 v[236:237], v[118:119], v[116:117] op_sel_hi:[1,0]
	v_add_f32_dpp v230, v230, v230 quad_perm:[1,0,3,2] row_mask:0xf bank_mask:0xf
	v_pk_mul_f32 v[238:239], v[118:119], v[116:117] op_sel:[0,1]
	ds_read_b128 v[222:225], v240 offset:42704
	v_add_f32_dpp v230, v230, v230 quad_perm:[2,3,0,1] row_mask:0xf bank_mask:0xf
	v_pk_fma_f32 v[232:233], v[206:207], v[102:103], v[232:233] op_sel_hi:[1,0,1]
	v_pk_fma_f32 v[234:235], v[208:209], v[102:103], v[234:235] op_sel:[0,1,0]
	v_add_f32_dpp v230, v230, v230 row_half_mirror row_mask:0xf bank_mask:0xf
	v_pk_fma_f32 v[236:237], v[210:211], v[104:105], v[236:237] op_sel_hi:[1,0,1]
	v_pk_fma_f32 v[238:239], v[212:213], v[104:105], v[238:239] op_sel:[0,1,0]
	v_mov_b32_dpp v231, v230 row_ror:8 row_mask:0xf bank_mask:0xf
	ds_write_b64 v217, v[228:229] offset:6336
	v_pk_fma_f32 v[206:207], v[110:111], v[230:231], v[232:233] op_sel_hi:[0,1,1] neg_lo:[1,0,0] neg_hi:[1,0,0]
	v_pk_fma_f32 v[208:209], v[110:111], v[230:231], v[234:235] op_sel:[1,0,0] neg_lo:[1,0,0] neg_hi:[1,0,0]
	v_pk_fma_f32 v[210:211], v[112:113], v[230:231], v[236:237] op_sel_hi:[0,1,1] neg_lo:[1,0,0] neg_hi:[1,0,0]
	v_pk_fma_f32 v[212:213], v[112:113], v[230:231], v[238:239] op_sel:[1,0,0] neg_lo:[1,0,0] neg_hi:[1,0,0]
	s_waitcnt lgkmcnt(8)
	ds_read_b128 v[106:109], v240 offset:17136
	ds_read_b64 v[118:119], v242 offset:51952
	ds_read_b128 v[114:117], v240 offset:34544
	ds_read_b128 v[102:105], v240 offset:8432
	ds_read_b128 v[110:113], v240 offset:25840
	v_pk_mul_f32 v[226:227], v[206:207], v[4:5] op_sel_hi:[1,0]
	v_pk_mul_f32 v[228:229], v[206:207], v[96:97] op_sel_hi:[1,0]
	v_pk_fma_f32 v[226:227], v[208:209], v[4:5], v[226:227] op_sel:[0,1,0]
	v_pk_fma_f32 v[228:229], v[208:209], v[96:97], v[228:229] op_sel:[0,1,0]
	v_pk_fma_f32 v[226:227], v[210:211], v[6:7], v[226:227] op_sel_hi:[1,0,1]
	v_pk_fma_f32 v[228:229], v[210:211], v[98:99], v[228:229] op_sel_hi:[1,0,1]
	v_pk_fma_f32 v[226:227], v[212:213], v[6:7], v[226:227] op_sel:[0,1,0]
	v_pk_fma_f32 v[228:229], v[212:213], v[98:99], v[228:229] op_sel:[0,1,0]
	v_pk_mul_f32 v[232:233], v[16:17], v[12:13] op_sel_hi:[1,0]
	v_add_f32_dpp v230, v227, v226 row_ror:8 row_mask:0xf bank_mask:0xf
	v_pk_mul_f32 v[234:235], v[16:17], v[12:13] op_sel:[0,1]
	v_pk_mul_f32 v[236:237], v[16:17], v[14:15] op_sel_hi:[1,0]
	v_add_f32_dpp v230, v230, v230 quad_perm:[1,0,3,2] row_mask:0xf bank_mask:0xf
	v_pk_mul_f32 v[238:239], v[16:17], v[14:15] op_sel:[0,1]
	ds_read_b128 v[96:99], v240 offset:42976
	v_add_f32_dpp v230, v230, v230 quad_perm:[2,3,0,1] row_mask:0xf bank_mask:0xf
	v_pk_fma_f32 v[232:233], v[206:207], v[0:1], v[232:233] op_sel_hi:[1,0,1]
	v_pk_fma_f32 v[234:235], v[208:209], v[0:1], v[234:235] op_sel:[0,1,0]
	v_add_f32_dpp v230, v230, v230 row_half_mirror row_mask:0xf bank_mask:0xf
	v_pk_fma_f32 v[236:237], v[210:211], v[2:3], v[236:237] op_sel_hi:[1,0,1]
	v_pk_fma_f32 v[238:239], v[212:213], v[2:3], v[238:239] op_sel:[0,1,0]
	v_mov_b32_dpp v231, v230 row_ror:8 row_mask:0xf bank_mask:0xf
	ds_write_b64 v217, v[228:229] offset:6912
	v_pk_fma_f32 v[206:207], v[8:9], v[230:231], v[232:233] op_sel_hi:[0,1,1] neg_lo:[1,0,0] neg_hi:[1,0,0]
	v_pk_fma_f32 v[208:209], v[8:9], v[230:231], v[234:235] op_sel:[1,0,0] neg_lo:[1,0,0] neg_hi:[1,0,0]
	v_pk_fma_f32 v[210:211], v[10:11], v[230:231], v[236:237] op_sel_hi:[0,1,1] neg_lo:[1,0,0] neg_hi:[1,0,0]
	v_pk_fma_f32 v[212:213], v[10:11], v[230:231], v[238:239] op_sel:[1,0,0] neg_lo:[1,0,0] neg_hi:[1,0,0]
	s_waitcnt lgkmcnt(8)
; __device__ __forceinline__ unsigned f2bf(float f) { unsigned u = __builtin_bit_cast(unsigned, f); return (u + 0x7fffu + ((u >> 16) & 1u)) >> 16; }
; template <int CTRL> __device__ __forceinline__ float dppf(float x) { return __builtin_bit_cast(float, __builtin_amdgcn_update_dpp(0, __builtin_bit_cast(int, x), CTRL, 0xF, 0xF, false)); }
; __device__ __forceinline__ void phase_rwkv_scan(const Fr& F, int jr) {
;     ...
;                         const int p = pg + pi, pn = p < 63 ? p + 1 : 63;
;                         const f32x4 w4n = PW[pn * 16], k4n = PW[1024 + pn * 16], b4n = PW[2048 + pn * 16], d4n = PW[3072 + pn * 16], r4n = PR[pn * 16];
;                         const float vvn = PV[pn * 32];
;                         f32x2 t = S01 * k4.xy; t = S23 * k4.zw + t; float sa = t.x + t.y;
;                         sa += dppf<0x128>(sa);
;                         const f32x2 dv01 = d4.xy * vv, dv23 = d4.zw * vv;
;                         sa += dppf<0x124>(sa);
;                         const f32x2 e01 = S01 * w4.xy + dv01;
;                         sa += dppf<0x122>(sa);
;                         const f32x2 e23 = S23 * w4.zw + dv23;
;                         sa += dppf<0x121>(sa);
;                         S01 = e01 - b4.xy * sa; S23 = e23 - b4.zw * sa;
;                         f32x2 u = S01 * r4.xy; u = S23 * r4.zw + u;
;                         PY[pi * 64] = u.x + u.y;
;                         w4 = w4n; k4 = k4n; b4 = b4n; d4 = d4n; r4 = r4n; vv = vvn;
;                     }
;                     asm volatile("s_waitcnt lgkmcnt(0)" ::: "memory");
;                     {
;                         const int j = lane >> 2, q = lane & 3; const float* yp = Ypw + j * 64 + q * 16;
;                         const f32x4 a0 = *(const f32x4*)yp, a1 = *(const f32x4*)(yp + 4), a2 = *(const f32x4*)(yp + 8), a3 = *(const f32x4*)(yp + 12);
;                         const f32x4 ssum = (a0 + a1) + (a2 + a3); const float yv = (ssum.x + ssum.y) + (ssum.z + ssum.w);
;                         const size_t row = (size_t)b * TB + tokof(s, chunk * 64 + pg + j);
;                         Yb[row * D + h * 64 + 32 * half + 4 * wave + q] = (bf16)f2bf(yv);
;                     }
	v_pk_mul_f32 v[226:227], v[206:207], v[84:85] op_sel_hi:[1,0]
	v_pk_mul_f32 v[228:229], v[206:207], v[222:223] op_sel_hi:[1,0]
	v_pk_fma_f32 v[226:227], v[208:209], v[84:85], v[226:227] op_sel:[0,1,0]
	v_pk_fma_f32 v[228:229], v[208:209], v[222:223], v[228:229] op_sel:[0,1,0]
	v_pk_fma_f32 v[226:227], v[210:211], v[86:87], v[226:227] op_sel_hi:[1,0,1]
	v_pk_fma_f32 v[228:229], v[210:211], v[224:225], v[228:229] op_sel_hi:[1,0,1]
	v_pk_fma_f32 v[226:227], v[212:213], v[86:87], v[226:227] op_sel:[0,1,0]
	v_pk_fma_f32 v[228:229], v[212:213], v[224:225], v[228:229] op_sel:[0,1,0]
	v_pk_mul_f32 v[232:233], v[100:101], v[92:93] op_sel_hi:[1,0]
	v_add_f32_dpp v230, v227, v226 row_ror:8 row_mask:0xf bank_mask:0xf
	v_pk_mul_f32 v[234:235], v[100:101], v[92:93] op_sel:[0,1]
	v_pk_mul_f32 v[236:237], v[100:101], v[94:95] op_sel_hi:[1,0]
	v_add_f32_dpp v230, v230, v230 quad_perm:[1,0,3,2] row_mask:0xf bank_mask:0xf
	v_pk_mul_f32 v[238:239], v[100:101], v[94:95] op_sel:[0,1]
	ds_read_b128 v[222:225], v240 offset:43248
	v_add_f32_dpp v230, v230, v230 quad_perm:[2,3,0,1] row_mask:0xf bank_mask:0xf
	v_pk_fma_f32 v[232:233], v[206:207], v[80:81], v[232:233] op_sel_hi:[1,0,1]
	v_pk_fma_f32 v[234:235], v[208:209], v[80:81], v[234:235] op_sel:[0,1,0]
	v_add_f32_dpp v230, v230, v230 row_half_mirror row_mask:0xf bank_mask:0xf
	v_pk_fma_f32 v[236:237], v[210:211], v[82:83], v[236:237] op_sel_hi:[1,0,1]
	v_pk_fma_f32 v[238:239], v[212:213], v[82:83], v[238:239] op_sel:[0,1,0]
	v_mov_b32_dpp v231, v230 row_ror:8 row_mask:0xf bank_mask:0xf
	ds_write_b64 v217, v[228:229] offset:7488
	v_pk_fma_f32 v[206:207], v[88:89], v[230:231], v[232:233] op_sel_hi:[0,1,1] neg_lo:[1,0,0] neg_hi:[1,0,0]
	v_pk_fma_f32 v[208:209], v[88:89], v[230:231], v[234:235] op_sel:[1,0,0] neg_lo:[1,0,0] neg_hi:[1,0,0]
	v_pk_fma_f32 v[210:211], v[90:91], v[230:231], v[236:237] op_sel_hi:[0,1,1] neg_lo:[1,0,0] neg_hi:[1,0,0]
	v_pk_fma_f32 v[212:213], v[90:91], v[230:231], v[238:239] op_sel:[1,0,0] neg_lo:[1,0,0] neg_hi:[1,0,0]
	s_waitcnt lgkmcnt(3)
	v_pk_mul_f32 v[226:227], v[206:207], v[106:107] op_sel_hi:[1,0]
	v_pk_mul_f32 v[228:229], v[206:207], v[96:97] op_sel_hi:[1,0]
	v_pk_fma_f32 v[226:227], v[208:209], v[106:107], v[226:227] op_sel:[0,1,0]
	v_pk_fma_f32 v[228:229], v[208:209], v[96:97], v[228:229] op_sel:[0,1,0]
	v_pk_fma_f32 v[226:227], v[210:211], v[108:109], v[226:227] op_sel_hi:[1,0,1]
	v_pk_fma_f32 v[228:229], v[210:211], v[98:99], v[228:229] op_sel_hi:[1,0,1]
	v_pk_fma_f32 v[226:227], v[212:213], v[108:109], v[226:227] op_sel:[0,1,0]
	v_pk_fma_f32 v[228:229], v[212:213], v[98:99], v[228:229] op_sel:[0,1,0]
	v_pk_mul_f32 v[232:233], v[118:119], v[114:115] op_sel_hi:[1,0]
	v_add_f32_dpp v230, v227, v226 row_ror:8 row_mask:0xf bank_mask:0xf
	v_pk_mul_f32 v[234:235], v[118:119], v[114:115] op_sel:[0,1]
	v_pk_mul_f32 v[236:237], v[118:119], v[116:117] op_sel_hi:[1,0]
	v_add_f32_dpp v230, v230, v230 quad_perm:[1,0,3,2] row_mask:0xf bank_mask:0xf
	v_pk_mul_f32 v[238:239], v[118:119], v[116:117] op_sel:[0,1]
	s_nop 0
	v_add_f32_dpp v230, v230, v230 quad_perm:[2,3,0,1] row_mask:0xf bank_mask:0xf
	v_pk_fma_f32 v[232:233], v[206:207], v[102:103], v[232:233] op_sel_hi:[1,0,1]
	v_pk_fma_f32 v[234:235], v[208:209], v[102:103], v[234:235] op_sel:[0,1,0]
	v_add_f32_dpp v230, v230, v230 row_half_mirror row_mask:0xf bank_mask:0xf
	v_pk_fma_f32 v[236:237], v[210:211], v[104:105], v[236:237] op_sel_hi:[1,0,1]
	v_pk_fma_f32 v[238:239], v[212:213], v[104:105], v[238:239] op_sel:[0,1,0]
	v_mov_b32_dpp v231, v230 row_ror:8 row_mask:0xf bank_mask:0xf
	ds_write_b64 v217, v[228:229] offset:8064
	v_pk_fma_f32 v[206:207], v[110:111], v[230:231], v[232:233] op_sel_hi:[0,1,1] neg_lo:[1,0,0] neg_hi:[1,0,0]
	v_pk_fma_f32 v[208:209], v[110:111], v[230:231], v[234:235] op_sel:[1,0,0] neg_lo:[1,0,0] neg_hi:[1,0,0]
	v_pk_fma_f32 v[210:211], v[112:113], v[230:231], v[236:237] op_sel_hi:[0,1,1] neg_lo:[1,0,0] neg_hi:[1,0,0]
	v_pk_fma_f32 v[212:213], v[112:113], v[230:231], v[238:239] op_sel:[1,0,0] neg_lo:[1,0,0] neg_hi:[1,0,0]
	s_waitcnt lgkmcnt(2)
	v_pk_mul_f32 v[228:229], v[206:207], v[222:223] op_sel_hi:[1,0]
	v_add_u32_e32 v243, s15, v219
	v_pk_fma_f32 v[228:229], v[208:209], v[222:223], v[228:229] op_sel:[0,1,0]
	v_lshl_add_u32 v243, v243, 11, v220
	v_pk_fma_f32 v[228:229], v[210:211], v[224:225], v[228:229] op_sel_hi:[1,0,1]
	s_nop 0
	v_pk_fma_f32 v[228:229], v[212:213], v[224:225], v[228:229] op_sel:[0,1,0]
	s_nop 0
	s_waitcnt lgkmcnt(1)
	ds_write_b64 v217, v[228:229] offset:8640
	ds_read_b128 v[24:27], v218 offset:0
	ds_read_b128 v[28:31], v218 offset:16
	ds_read_b128 v[32:35], v218 offset:32
	ds_read_b128 v[36:39], v218 offset:48
	ds_read_b128 v[40:43], v218 offset:64
	ds_read_b128 v[44:47], v218 offset:80
	ds_read_b128 v[48:51], v218 offset:96
	s_waitcnt lgkmcnt(5)
	ds_read_b128 v[52:55], v218 offset:112
	v_pk_add_f32 v[24:25], v[24:25], v[26:27]
	v_pk_add_f32 v[28:29], v[28:29], v[30:31]
	s_waitcnt lgkmcnt(4)
	v_pk_add_f32 v[32:33], v[32:33], v[34:35]
	v_pk_add_f32 v[36:37], v[36:37], v[38:39]
	v_pk_add_f32 v[24:25], v[24:25], v[28:29]
	s_waitcnt lgkmcnt(2)
	v_pk_add_f32 v[40:41], v[40:41], v[42:43]
	v_pk_add_f32 v[44:45], v[44:45], v[46:47]
	v_pk_add_f32 v[32:33], v[32:33], v[36:37]
	s_waitcnt lgkmcnt(0)
	v_pk_add_f32 v[48:49], v[48:49], v[50:51]
	v_pk_add_f32 v[52:53], v[52:53], v[54:55]
	v_pk_add_f32 v[40:41], v[40:41], v[44:45]
	v_pk_add_f32 v[24:25], v[24:25], v[32:33]
	v_pk_add_f32 v[48:49], v[48:49], v[52:53]
	s_add_i32 s15, s15, s19
	v_pk_add_f32 v[40:41], v[40:41], v[48:49]
	s_nop 0
	v_pk_add_f32 v[24:25], v[24:25], v[40:41] op_sel:[0,1] op_sel_hi:[1,0]
	s_nop 0
	v_cvt_pk_bf16_f32 v244, v24, v25
	s_nop 0
	global_store_dword v243, v244, s[20:21]
	s_waitcnt lgkmcnt(0)
	s_add_i32 s10, s10, 1
	s_xor_b32 s11, s11, 0xcc00
	s_barrier
	s_cmp_lt_u32 s10, 136
	s_cbranch_scc1 .Lrw0_shc
	s_setprio 0
	s_branch .Lrw0_end
